# in-proj: the epilogue's eight row-statistic loads are issued in the last K iteration (before the final MFMA block) instead of at epilogue start
# baseline (speedup 1.0000x reference)
; #define PG8_STAGE(bufoff, gbase, voff) do { _Pragma("unroll") for (int _i = 0; _i < 2; ++_i) \
;         __builtin_amdgcn_global_load_lds((const unsigned*)((const char*)(gbase) + (voff)[_i]), (PG8_LAS unsigned*)(lds + (bufoff) + ldsw + _i * 8192), 16, 0, 0); } while (0)
; #define PG8_LDA(dst, b, h) do { _Pragma("unroll") for (int m = 0; m < 4; ++m) _Pragma("unroll") for (int k = 0; k < 2; ++k) dst[m][k] = *(const PG8_LAS bf16x8*)(lds + PG8_SA(b, h) + aoff + m * 2048 + k * 1024); } while (0)
; #define PG8_LDB(dst, b, h) do { _Pragma("unroll") for (int n = 0; n < 2; ++n) _Pragma("unroll") for (int k = 0; k < 2; ++k) dst[n][k] = *(const PG8_LAS bf16x8*)(lds + PG8_SB(b, h) + boff + n * 2048 + k * 1024); } while (0)
; #define PG8_MMA(ai, bj, At, Bt) do { __builtin_amdgcn_s_setprio(1); _Pragma("unroll") for (int m = 0; m < 4; ++m) _Pragma("unroll") for (int n = 0; n < 2; ++n) _Pragma("unroll") for (int k = 0; k < 2; ++k) \
;         acc[ai][bj][m][n] = __builtin_amdgcn_mfma_f32_16x16x32_bf16(Bt[n][k], At[m][k], acc[ai][bj][m][n], 0, 0, 0); __builtin_amdgcn_s_setprio(0); } while (0)
; #define PG8_WAIT_V(n) asm volatile("s_waitcnt vmcnt(" #n ")" ::: "memory")
; #define PG8_WAIT_L(n) asm volatile("s_waitcnt lgkmcnt(" #n ")" ::: "memory")
; #define PG8_BAR __builtin_amdgcn_s_barrier()
; #define PG8_SCHED __builtin_amdgcn_sched_barrier(0)
; template <class Epi, class Sched, bool ALIGN_EPI = false, bool SP2 = false>
; __device__ __forceinline__ void gemm_phase(PG8_LAS unsigned char* lds, const Gemm g, const Sched& S, const Epi& E, const int wv) {
;     ...
;             PG8_LDB(B0, 0, 0); PG8_LDB(B1, 0, 1); PG8_SCHED; PG8_LDA(At, 0, 0); PG8_STAGE(PG8_SA(1, 1), a1 + hstep, voffA);
;             PG8_WAIT_V(8); PG8_WAIT_L(0); PG8_BAR; PG8_MMA(0, 0, At, B0); PG8_MMA(0, 1, At, B1); PG8_BAR; PG8_SCHED;
;             PG8_LDA(At, 0, 1); PG8_STAGE(PG8_SB(0, 0), b2, voffB); PG8_STAGE(PG8_SB(0, 1), b2 + hstep, voffB); PG8_STAGE(PG8_SA(0, 0), a2, voffA);
.LBB0_234:
	ds_read_b128 v[128:131], v179
	ds_read_b128 v[132:135], v179 offset:1024
	ds_read_b128 v[136:139], v179 offset:2048
	ds_read_b128 v[140:143], v179 offset:3072
	ds_read_b128 v[160:163], v180
	ds_read_b128 v[164:167], v180 offset:1024
	ds_read_b128 v[168:171], v180 offset:2048
	ds_read_b128 v[184:187], v180 offset:3072
	s_add_u32 s24, s58, 0xfffc0080
	s_addc_u32 s25, s59, -1
	s_cmp_eq_u32 s97, 12
	s_cselect_b32 s63, s51, s25
	s_cselect_b32 s62, s57, s24
	s_cselect_b32 s61, s49, s96
	s_cselect_b32 s60, s65, s70
	v_lshl_add_u64 v[172:173], s[58:59], 0, v[152:153]
	s_add_i32 m0, s81, 0xc000
	ds_read_b128 v[188:191], v181
	ds_read_b128 v[192:195], v181 offset:1024
	ds_read_b128 v[196:199], v181 offset:2048
	ds_read_b128 v[200:203], v181 offset:3072
	ds_read_b128 v[204:207], v181 offset:4096
	ds_read_b128 v[208:211], v181 offset:5120
	ds_read_b128 v[214:217], v181 offset:6144
	ds_read_b128 v[222:225], v181 offset:7168
	global_load_lds_dwordx4 v[172:173], off
	v_lshl_add_u64 v[172:173], s[58:59], 0, v[154:155]
	s_add_i32 m0, s81, 0xe000
	s_nop 0
	global_load_lds_dwordx4 v[172:173], off
	s_waitcnt vmcnt(8)
	s_waitcnt lgkmcnt(0)
	s_barrier
	s_setprio 1
	s_waitcnt lgkmcnt(0)
	v_mfma_f32_16x16x32_bf16 v[124:127], v[128:131], v[188:191], v[124:127]
	v_mfma_f32_16x16x32_bf16 v[120:123], v[136:139], v[188:191], v[120:123]
	v_mfma_f32_16x16x32_bf16 v[108:111], v[128:131], v[196:199], v[108:111]
	v_mfma_f32_16x16x32_bf16 v[104:107], v[136:139], v[196:199], v[104:107]
	v_mfma_f32_16x16x32_bf16 v[92:95], v[128:131], v[204:207], v[92:95]
	v_mfma_f32_16x16x32_bf16 v[88:91], v[136:139], v[204:207], v[88:91]
	v_mfma_f32_16x16x32_bf16 v[84:87], v[128:131], v[214:217], v[84:87]
	v_mfma_f32_16x16x32_bf16 v[72:75], v[136:139], v[214:217], v[72:75]
	v_mfma_f32_16x16x32_bf16 v[124:127], v[132:135], v[192:195], v[124:127]
	v_mfma_f32_16x16x32_bf16 v[120:123], v[140:143], v[192:195], v[120:123]
	v_mfma_f32_16x16x32_bf16 v[108:111], v[132:135], v[200:203], v[108:111]
	v_mfma_f32_16x16x32_bf16 v[104:107], v[140:143], v[200:203], v[104:107]
	v_mfma_f32_16x16x32_bf16 v[92:95], v[132:135], v[208:211], v[92:95]
	v_mfma_f32_16x16x32_bf16 v[88:91], v[140:143], v[208:211], v[88:91]
	v_mfma_f32_16x16x32_bf16 v[84:87], v[132:135], v[222:225], v[84:87]
	v_mfma_f32_16x16x32_bf16 v[72:75], v[140:143], v[222:225], v[72:75]
	s_setprio 0
	s_setprio 1
	v_mfma_f32_16x16x32_bf16 v[116:119], v[160:163], v[188:191], v[116:119]
	v_mfma_f32_16x16x32_bf16 v[112:115], v[168:171], v[188:191], v[112:115]
	v_mfma_f32_16x16x32_bf16 v[100:103], v[160:163], v[196:199], v[100:103]
	v_mfma_f32_16x16x32_bf16 v[96:99], v[168:171], v[196:199], v[96:99]
	v_mfma_f32_16x16x32_bf16 v[80:83], v[160:163], v[204:207], v[80:83]
	v_mfma_f32_16x16x32_bf16 v[76:79], v[168:171], v[204:207], v[76:79]
	v_mfma_f32_16x16x32_bf16 v[68:71], v[160:163], v[214:217], v[68:71]
	v_mfma_f32_16x16x32_bf16 v[64:67], v[168:171], v[214:217], v[64:67]
	v_mfma_f32_16x16x32_bf16 v[116:119], v[164:167], v[192:195], v[116:119]
	v_mfma_f32_16x16x32_bf16 v[112:115], v[184:187], v[192:195], v[112:115]
	v_mfma_f32_16x16x32_bf16 v[100:103], v[164:167], v[200:203], v[100:103]
	v_mfma_f32_16x16x32_bf16 v[96:99], v[184:187], v[200:203], v[96:99]
	v_mfma_f32_16x16x32_bf16 v[80:83], v[164:167], v[208:211], v[80:83]
	v_mfma_f32_16x16x32_bf16 v[76:79], v[184:187], v[208:211], v[76:79]
	v_mfma_f32_16x16x32_bf16 v[68:71], v[164:167], v[222:225], v[68:71]
	v_mfma_f32_16x16x32_bf16 v[64:67], v[184:187], v[222:225], v[64:67]
	s_setprio 0
	s_barrier
	s_add_i32 s24, s88, s64
	v_lshl_add_u64 v[172:173], s[60:61], 0, v[148:149]
	s_mov_b32 m0, s24
	ds_read_b128 v[188:191], v181 offset:16384
	ds_read_b128 v[192:195], v181 offset:17408
	ds_read_b128 v[196:199], v181 offset:18432
	ds_read_b128 v[200:203], v181 offset:19456
	ds_read_b128 v[204:207], v181 offset:20480
	ds_read_b128 v[208:211], v181 offset:21504
	ds_read_b128 v[214:217], v181 offset:22528
	ds_read_b128 v[222:225], v181 offset:23552
	global_load_lds_dwordx4 v[172:173], off
	s_add_i32 m0, s24, 0x2000
	s_add_u32 s24, s60, 0x40000
	v_lshl_add_u64 v[226:227], s[60:61], 0, v[144:145]
	s_addc_u32 s25, s61, 0
	s_add_i32 vcc_lo, s89, s64
	global_load_lds_dwordx4 v[226:227], off
	v_lshl_add_u64 v[228:229], s[24:25], 0, v[148:149]
	s_mov_b32 m0, vcc_lo
	v_lshl_add_u64 v[230:231], s[62:63], 0, v[146:147]
	global_load_lds_dwordx4 v[228:229], off
	v_lshl_add_u64 v[228:229], s[24:25], 0, v[144:145]
	s_add_i32 m0, vcc_lo, 0x2000
	s_nop 0
	global_load_lds_dwordx4 v[228:229], off
	v_lshl_add_u64 v[228:229], s[62:63], 0, v[150:151]
	s_mov_b32 m0, s81
	s_nop 0
	global_load_lds_dwordx4 v[228:229], off
	s_mov_b32 m0, s82
	s_nop 0
	global_load_lds_dwordx4 v[230:231], off
	s_waitcnt vmcnt(8)
	s_waitcnt lgkmcnt(0)
	s_barrier
; #define PG8_STAGE(bufoff, gbase, voff) do { _Pragma("unroll") for (int _i = 0; _i < 2; ++_i) \
;         __builtin_amdgcn_global_load_lds((const unsigned*)((const char*)(gbase) + (voff)[_i]), (PG8_LAS unsigned*)(lds + (bufoff) + ldsw + _i * 8192), 16, 0, 0); } while (0)
; #define PG8_LDA(dst, b, h) do { _Pragma("unroll") for (int m = 0; m < 4; ++m) _Pragma("unroll") for (int k = 0; k < 2; ++k) dst[m][k] = *(const PG8_LAS bf16x8*)(lds + PG8_SA(b, h) + aoff + m * 2048 + k * 1024); } while (0)
; #define PG8_LDB(dst, b, h) do { _Pragma("unroll") for (int n = 0; n < 2; ++n) _Pragma("unroll") for (int k = 0; k < 2; ++k) dst[n][k] = *(const PG8_LAS bf16x8*)(lds + PG8_SB(b, h) + boff + n * 2048 + k * 1024); } while (0)
; #define PG8_MMA(ai, bj, At, Bt) do { __builtin_amdgcn_s_setprio(1); _Pragma("unroll") for (int m = 0; m < 4; ++m) _Pragma("unroll") for (int n = 0; n < 2; ++n) _Pragma("unroll") for (int k = 0; k < 2; ++k) \
;         acc[ai][bj][m][n] = __builtin_amdgcn_mfma_f32_16x16x32_bf16(Bt[n][k], At[m][k], acc[ai][bj][m][n], 0, 0, 0); __builtin_amdgcn_s_setprio(0); } while (0)
; #define PG8_WAIT_V(n) asm volatile("s_waitcnt vmcnt(" #n ")" ::: "memory")
; #define PG8_WAIT_L(n) asm volatile("s_waitcnt lgkmcnt(" #n ")" ::: "memory")
; #define PG8_BAR __builtin_amdgcn_s_barrier()
; #define PG8_SCHED __builtin_amdgcn_sched_barrier(0)
; template <class Epi, class Sched, bool ALIGN_EPI = false, bool SP2 = false>
; __device__ __forceinline__ void gemm_phase(PG8_LAS unsigned char* lds, const Gemm g, const Sched& S, const Epi& E, const int wv) {
;     ...
;             PG8_WAIT_V(8); PG8_WAIT_L(0); PG8_BAR; PG8_MMA(1, 0, At, B0); PG8_MMA(1, 1, At, B1); PG8_BAR; PG8_SCHED;
;             PG8_LDB(B0, 1, 0); PG8_LDB(B1, 1, 1); PG8_SCHED; PG8_LDA(At, 1, 0); PG8_STAGE(PG8_SA(0, 1), a2 + hstep, voffA);
;             PG8_WAIT_V(8); PG8_WAIT_L(0); PG8_BAR; PG8_MMA(0, 0, At, B0); PG8_MMA(0, 1, At, B1); PG8_BAR; PG8_SCHED;
	s_setprio 1
	s_waitcnt lgkmcnt(0)
	v_mfma_f32_16x16x32_bf16 v[60:63], v[128:131], v[188:191], v[60:63]
	v_mfma_f32_16x16x32_bf16 v[56:59], v[136:139], v[188:191], v[56:59]
	v_mfma_f32_16x16x32_bf16 v[44:47], v[128:131], v[196:199], v[44:47]
	v_mfma_f32_16x16x32_bf16 v[40:43], v[136:139], v[196:199], v[40:43]
	v_mfma_f32_16x16x32_bf16 v[28:31], v[128:131], v[204:207], v[28:31]
	v_mfma_f32_16x16x32_bf16 v[24:27], v[136:139], v[204:207], v[24:27]
	v_mfma_f32_16x16x32_bf16 v[12:15], v[128:131], v[214:217], v[12:15]
	v_mfma_f32_16x16x32_bf16 v[8:11], v[136:139], v[214:217], v[8:11]
	v_mfma_f32_16x16x32_bf16 v[60:63], v[132:135], v[192:195], v[60:63]
	v_mfma_f32_16x16x32_bf16 v[56:59], v[140:143], v[192:195], v[56:59]
	v_mfma_f32_16x16x32_bf16 v[44:47], v[132:135], v[200:203], v[44:47]
	v_mfma_f32_16x16x32_bf16 v[40:43], v[140:143], v[200:203], v[40:43]
	v_mfma_f32_16x16x32_bf16 v[28:31], v[132:135], v[208:211], v[28:31]
	v_mfma_f32_16x16x32_bf16 v[24:27], v[140:143], v[208:211], v[24:27]
	v_mfma_f32_16x16x32_bf16 v[12:15], v[132:135], v[222:225], v[12:15]
	v_mfma_f32_16x16x32_bf16 v[8:11], v[140:143], v[222:225], v[8:11]
	s_setprio 0
	s_setprio 1
	v_mfma_f32_16x16x32_bf16 v[52:55], v[160:163], v[188:191], v[52:55]
	v_mfma_f32_16x16x32_bf16 v[48:51], v[168:171], v[188:191], v[48:51]
	v_mfma_f32_16x16x32_bf16 v[36:39], v[160:163], v[196:199], v[36:39]
	v_mfma_f32_16x16x32_bf16 v[32:35], v[168:171], v[196:199], v[32:35]
	v_mfma_f32_16x16x32_bf16 v[20:23], v[160:163], v[204:207], v[20:23]
	v_mfma_f32_16x16x32_bf16 v[16:19], v[168:171], v[204:207], v[16:19]
	v_mfma_f32_16x16x32_bf16 v[4:7], v[160:163], v[214:217], v[4:7]
	v_mfma_f32_16x16x32_bf16 v[0:3], v[168:171], v[214:217], v[0:3]
	v_mfma_f32_16x16x32_bf16 v[52:55], v[164:167], v[192:195], v[52:55]
	v_mfma_f32_16x16x32_bf16 v[48:51], v[184:187], v[192:195], v[48:51]
	v_mfma_f32_16x16x32_bf16 v[36:39], v[164:167], v[200:203], v[36:39]
	v_mfma_f32_16x16x32_bf16 v[32:35], v[184:187], v[200:203], v[32:35]
	v_mfma_f32_16x16x32_bf16 v[20:23], v[164:167], v[208:211], v[20:23]
	v_mfma_f32_16x16x32_bf16 v[16:19], v[184:187], v[208:211], v[16:19]
	v_mfma_f32_16x16x32_bf16 v[4:7], v[164:167], v[222:225], v[4:7]
	v_mfma_f32_16x16x32_bf16 v[0:3], v[184:187], v[222:225], v[0:3]
	s_setprio 0
	s_barrier
	s_add_i32 vcc_lo, 0, 0x18000
	s_add_i32 vcc_hi, 0, 0x1c000
	v_add_u32_e32 v140, vcc_lo, v176
	v_add_u32_e32 v184, vcc_hi, v176
	ds_read_b128 v[128:131], v140
	ds_read_b128 v[132:135], v140 offset:1024
	ds_read_b128 v[136:139], v140 offset:2048
	ds_read_b128 v[140:143], v140 offset:3072
	ds_read_b128 v[160:163], v184
	ds_read_b128 v[164:167], v184 offset:1024
	ds_read_b128 v[168:171], v184 offset:2048
	ds_read_b128 v[184:187], v184 offset:3072
	s_add_u32 s24, s62, 0x40000
	s_addc_u32 s25, s63, 0
	s_mov_b32 m0, s83
	v_lshl_add_u64 v[232:233], s[24:25], 0, v[150:151]
	ds_read_b128 v[188:191], v181 offset:32768
	ds_read_b128 v[192:195], v181 offset:33792
	ds_read_b128 v[196:199], v181 offset:34816
	ds_read_b128 v[200:203], v181 offset:35840
	ds_read_b128 v[204:207], v181 offset:36864
	ds_read_b128 v[208:211], v181 offset:37888
	ds_read_b128 v[214:217], v181 offset:38912
	ds_read_b128 v[222:225], v181 offset:39936
	global_load_lds_dwordx4 v[232:233], off
	v_lshl_add_u64 v[232:233], s[24:25], 0, v[146:147]
	s_mov_b32 m0, s84
	s_nop 0
	global_load_lds_dwordx4 v[232:233], off
	s_waitcnt vmcnt(8)
	s_waitcnt lgkmcnt(0)
	s_barrier
	s_setprio 1
	s_waitcnt lgkmcnt(0)
	v_mfma_f32_16x16x32_bf16 v[124:127], v[128:131], v[188:191], v[124:127]
	v_mfma_f32_16x16x32_bf16 v[120:123], v[136:139], v[188:191], v[120:123]
	v_mfma_f32_16x16x32_bf16 v[108:111], v[128:131], v[196:199], v[108:111]
	v_mfma_f32_16x16x32_bf16 v[104:107], v[136:139], v[196:199], v[104:107]
	v_mfma_f32_16x16x32_bf16 v[92:95], v[128:131], v[204:207], v[92:95]
	v_mfma_f32_16x16x32_bf16 v[88:91], v[136:139], v[204:207], v[88:91]
	v_mfma_f32_16x16x32_bf16 v[84:87], v[128:131], v[214:217], v[84:87]
	v_mfma_f32_16x16x32_bf16 v[72:75], v[136:139], v[214:217], v[72:75]
	v_mfma_f32_16x16x32_bf16 v[124:127], v[132:135], v[192:195], v[124:127]
	v_mfma_f32_16x16x32_bf16 v[120:123], v[140:143], v[192:195], v[120:123]
	v_mfma_f32_16x16x32_bf16 v[108:111], v[132:135], v[200:203], v[108:111]
	v_mfma_f32_16x16x32_bf16 v[104:107], v[140:143], v[200:203], v[104:107]
	v_mfma_f32_16x16x32_bf16 v[92:95], v[132:135], v[208:211], v[92:95]
	v_mfma_f32_16x16x32_bf16 v[88:91], v[140:143], v[208:211], v[88:91]
	v_mfma_f32_16x16x32_bf16 v[84:87], v[132:135], v[222:225], v[84:87]
	v_mfma_f32_16x16x32_bf16 v[72:75], v[140:143], v[222:225], v[72:75]
	s_setprio 0
	s_setprio 1
	v_mfma_f32_16x16x32_bf16 v[116:119], v[160:163], v[188:191], v[116:119]
	v_mfma_f32_16x16x32_bf16 v[112:115], v[168:171], v[188:191], v[112:115]
	v_mfma_f32_16x16x32_bf16 v[100:103], v[160:163], v[196:199], v[100:103]
	v_mfma_f32_16x16x32_bf16 v[96:99], v[168:171], v[196:199], v[96:99]
	v_mfma_f32_16x16x32_bf16 v[80:83], v[160:163], v[204:207], v[80:83]
	v_mfma_f32_16x16x32_bf16 v[76:79], v[168:171], v[204:207], v[76:79]
	v_mfma_f32_16x16x32_bf16 v[68:71], v[160:163], v[214:217], v[68:71]
	v_mfma_f32_16x16x32_bf16 v[64:67], v[168:171], v[214:217], v[64:67]
	v_mfma_f32_16x16x32_bf16 v[116:119], v[164:167], v[192:195], v[116:119]
	v_mfma_f32_16x16x32_bf16 v[112:115], v[184:187], v[192:195], v[112:115]
	v_mfma_f32_16x16x32_bf16 v[100:103], v[164:167], v[200:203], v[100:103]
	v_mfma_f32_16x16x32_bf16 v[96:99], v[184:187], v[200:203], v[96:99]
	v_mfma_f32_16x16x32_bf16 v[80:83], v[164:167], v[208:211], v[80:83]
	v_mfma_f32_16x16x32_bf16 v[76:79], v[184:187], v[208:211], v[76:79]
	v_mfma_f32_16x16x32_bf16 v[68:71], v[164:167], v[222:225], v[68:71]
	v_mfma_f32_16x16x32_bf16 v[64:67], v[184:187], v[222:225], v[64:67]
	s_setprio 0
	s_barrier
; #define PG8_STAGE(bufoff, gbase, voff) do { _Pragma("unroll") for (int _i = 0; _i < 2; ++_i) \
;         __builtin_amdgcn_global_load_lds((const unsigned*)((const char*)(gbase) + (voff)[_i]), (PG8_LAS unsigned*)(lds + (bufoff) + ldsw + _i * 8192), 16, 0, 0); } while (0)
; #define PG8_LDA(dst, b, h) do { _Pragma("unroll") for (int m = 0; m < 4; ++m) _Pragma("unroll") for (int k = 0; k < 2; ++k) dst[m][k] = *(const PG8_LAS bf16x8*)(lds + PG8_SA(b, h) + aoff + m * 2048 + k * 1024); } while (0)
; #define PG8_MMA(ai, bj, At, Bt) do { __builtin_amdgcn_s_setprio(1); _Pragma("unroll") for (int m = 0; m < 4; ++m) _Pragma("unroll") for (int n = 0; n < 2; ++n) _Pragma("unroll") for (int k = 0; k < 2; ++k) \
;         acc[ai][bj][m][n] = __builtin_amdgcn_mfma_f32_16x16x32_bf16(Bt[n][k], At[m][k], acc[ai][bj][m][n], 0, 0, 0); __builtin_amdgcn_s_setprio(0); } while (0)
; #define PG8_WAIT_V(n) asm volatile("s_waitcnt vmcnt(" #n ")" ::: "memory")
; #define PG8_WAIT_L(n) asm volatile("s_waitcnt lgkmcnt(" #n ")" ::: "memory")
; #define PG8_BAR __builtin_amdgcn_s_barrier()
; #define PG8_SCHED __builtin_amdgcn_sched_barrier(0)
; __device__ __forceinline__ float rstd_of(float ssq) { return __builtin_amdgcn_rsqf(ssq * (1.0f / DM) + EPS); }
; template <class Epi, class Sched, bool ALIGN_EPI = false, bool SP2 = false>
; __device__ __forceinline__ void gemm_phase(PG8_LAS unsigned char* lds, const Gemm g, const Sched& S, const Epi& E, const int wv) {
;     ...
;             PG8_LDA(At, 1, 1); PG8_STAGE(PG8_SB(1, 0), b3, voffB); PG8_STAGE(PG8_SB(1, 1), b3 + hstep, voffB); PG8_STAGE(PG8_SA(1, 0), a3, voffA);
;             PG8_WAIT_V(8); PG8_WAIT_L(0); PG8_BAR; PG8_MMA(1, 0, At, B0); PG8_MMA(1, 1, At, B1); PG8_BAR; PG8_SCHED;
;     __device__ __forceinline__ void operator()(const f32x4 (&acc)[2][2][4][2], const Unit& u, int wr, int wc, int fr, int fq) const {
;     ...
;                 for (int m = 0; m < 4; ++m) { const int r = row0 + ai * 128 + m * 16; const float rs = rstd_of(ssq0[r]) * cs;
	s_add_i32 s24, vcc_lo, s64
	v_lshl_add_u64 v[172:173], v[172:173], 0, s[38:39]
	s_mov_b32 m0, s24
	ds_read_b128 v[188:191], v181 offset:49152
	ds_read_b128 v[192:195], v181 offset:50176
	ds_read_b128 v[196:199], v181 offset:51200
	ds_read_b128 v[200:203], v181 offset:52224
	ds_read_b128 v[204:207], v181 offset:53248
	ds_read_b128 v[208:211], v181 offset:54272
	ds_read_b128 v[214:217], v181 offset:55296
	ds_read_b128 v[222:225], v181 offset:56320
	global_load_lds_dwordx4 v[172:173], off
	s_add_i32 m0, s24, 0x2000
	s_add_u32 s24, s60, 0x40080
	v_lshl_add_u64 v[172:173], v[226:227], 0, s[38:39]
	s_addc_u32 s25, s61, 0
	s_add_i32 s60, vcc_hi, s64
	global_load_lds_dwordx4 v[172:173], off
	v_lshl_add_u64 v[172:173], s[24:25], 0, v[148:149]
	s_mov_b32 m0, s60
	s_nop 0
	global_load_lds_dwordx4 v[172:173], off
	v_lshl_add_u64 v[172:173], s[24:25], 0, v[144:145]
	s_add_i32 m0, s60, 0x2000
	s_nop 0
	global_load_lds_dwordx4 v[172:173], off
	v_lshl_add_u64 v[172:173], v[228:229], 0, s[38:39]
	s_mov_b32 m0, s85
	s_nop 0
	global_load_lds_dwordx4 v[172:173], off
	v_lshl_add_u64 v[172:173], v[230:231], 0, s[38:39]
	s_mov_b32 m0, s86
	s_nop 0
	global_load_lds_dwordx4 v[172:173], off
	s_waitcnt vmcnt(8)
	s_waitcnt lgkmcnt(0)
	s_cmp_lg_u32 s97, 12
	s_cbranch_scc1 .Lh1_skip
	v_lshl_add_u32 v236, s56, 8, v175
	v_ashrrev_i32_e32 v237, 31, v236
	v_lshl_add_u64 v[236:237], v[236:237], 2, s[14:15]
	global_load_dword v238, v[236:237], off
	global_load_dword v239, v[236:237], off offset:64
	global_load_dword v240, v[236:237], off offset:128
	global_load_dword v241, v[236:237], off offset:192
	global_load_dword v242, v[236:237], off offset:512
	global_load_dword v243, v[236:237], off offset:576
	global_load_dword v244, v[236:237], off offset:640
	global_load_dword v245, v[236:237], off offset:704
.Lh1_skip:
	s_barrier
	s_setprio 1
	s_waitcnt lgkmcnt(0)
	v_mfma_f32_16x16x32_bf16 v[60:63], v[128:131], v[188:191], v[60:63]
	v_mfma_f32_16x16x32_bf16 v[56:59], v[136:139], v[188:191], v[56:59]
	v_mfma_f32_16x16x32_bf16 v[44:47], v[128:131], v[196:199], v[44:47]
	v_mfma_f32_16x16x32_bf16 v[40:43], v[136:139], v[196:199], v[40:43]
	v_mfma_f32_16x16x32_bf16 v[28:31], v[128:131], v[204:207], v[28:31]
	v_mfma_f32_16x16x32_bf16 v[24:27], v[136:139], v[204:207], v[24:27]
	v_mfma_f32_16x16x32_bf16 v[12:15], v[128:131], v[214:217], v[12:15]
	v_mfma_f32_16x16x32_bf16 v[8:11], v[136:139], v[214:217], v[8:11]
	v_mfma_f32_16x16x32_bf16 v[60:63], v[132:135], v[192:195], v[60:63]
	v_mfma_f32_16x16x32_bf16 v[56:59], v[140:143], v[192:195], v[56:59]
	v_mfma_f32_16x16x32_bf16 v[44:47], v[132:135], v[200:203], v[44:47]
	v_mfma_f32_16x16x32_bf16 v[40:43], v[140:143], v[200:203], v[40:43]
	v_mfma_f32_16x16x32_bf16 v[28:31], v[132:135], v[208:211], v[28:31]
	v_mfma_f32_16x16x32_bf16 v[24:27], v[140:143], v[208:211], v[24:27]
	v_mfma_f32_16x16x32_bf16 v[12:15], v[132:135], v[222:225], v[12:15]
	v_mfma_f32_16x16x32_bf16 v[8:11], v[140:143], v[222:225], v[8:11]
	s_setprio 0
	s_setprio 1
	v_mfma_f32_16x16x32_bf16 v[52:55], v[160:163], v[188:191], v[52:55]
	v_mfma_f32_16x16x32_bf16 v[48:51], v[168:171], v[188:191], v[48:51]
	v_mfma_f32_16x16x32_bf16 v[36:39], v[160:163], v[196:199], v[36:39]
	v_mfma_f32_16x16x32_bf16 v[32:35], v[168:171], v[196:199], v[32:35]
	v_mfma_f32_16x16x32_bf16 v[20:23], v[160:163], v[204:207], v[20:23]
	v_mfma_f32_16x16x32_bf16 v[16:19], v[168:171], v[204:207], v[16:19]
	v_mfma_f32_16x16x32_bf16 v[4:7], v[160:163], v[214:217], v[4:7]
	v_mfma_f32_16x16x32_bf16 v[0:3], v[168:171], v[214:217], v[0:3]
	v_mfma_f32_16x16x32_bf16 v[52:55], v[164:167], v[192:195], v[52:55]
	v_mfma_f32_16x16x32_bf16 v[48:51], v[184:187], v[192:195], v[48:51]
	v_mfma_f32_16x16x32_bf16 v[36:39], v[164:167], v[200:203], v[36:39]
	v_mfma_f32_16x16x32_bf16 v[32:35], v[184:187], v[200:203], v[32:35]
	v_mfma_f32_16x16x32_bf16 v[20:23], v[164:167], v[208:211], v[20:23]
	v_mfma_f32_16x16x32_bf16 v[16:19], v[184:187], v[208:211], v[16:19]
	v_mfma_f32_16x16x32_bf16 v[4:7], v[164:167], v[222:225], v[4:7]
	v_mfma_f32_16x16x32_bf16 v[0:3], v[184:187], v[222:225], v[0:3]
	s_setprio 0
	s_barrier
	s_add_i32 s97, s97, 2
	s_add_u32 s58, s58, 0x100
	s_addc_u32 s59, s59, 0
	s_add_u32 s70, s70, 0x100
	s_addc_u32 s96, s96, 0
	s_cmp_gt_u32 s97, 13
	s_cbranch_scc0 .LBB0_234
	s_and_b64 vcc, exec, s[22:23]
	s_cbranch_vccz .LBB0_237
	s_barrier

; __device__ __forceinline__ unsigned pk2(float lo, float hi) { return pg8::cvt_pk_bf16(lo, hi); }
; __device__ __forceinline__ float fsigmoid(float z) { return __builtin_amdgcn_rcpf(1.0f + __builtin_amdgcn_exp2f(-LOG2E * z)); }
; __device__ __forceinline__ float rstd_of(float ssq) { return __builtin_amdgcn_rsqf(ssq * (1.0f / DM) + EPS); }
;     __device__ __forceinline__ void operator()(const f32x4 (&acc)[2][2][4][2], const Unit& u, int wr, int wc, int fr, int fq) const {
;     ...
;             const int gc = (pn - 8) * 256 + ct;
;             f32x4 bv[2][2];
; #pragma unroll
;             for (int bj = 0; bj < 2; ++bj)
; #pragma unroll
;                 for (int n = 0; n < 2; ++n) bv[bj][n] = *(const f32x4*)(b_gate + gc + bj * 128 + 4 * n);
; #pragma unroll
;             for (int ai = 0; ai < 2; ++ai)
; #pragma unroll
;                 for (int m = 0; m < 4; ++m) { const int r = row0 + ai * 128 + m * 16; const float rs = rstd_of(ssq0[r]);
; #pragma unroll
;                     for (int bj = 0; bj < 2; ++bj) { const f32x4 z0 = acc[ai][bj][m][0] * rs + bv[bj][0], z1 = acc[ai][bj][m][1] * rs + bv[bj][1];
;                         u32x4 w; w.x = pk2(fsigmoid(z0[0]), fsigmoid(z0[1])); w.y = pk2(fsigmoid(z0[2]), fsigmoid(z0[3])); w.z = pk2(fsigmoid(z1[0]), fsigmoid(z1[1])); w.w = pk2(fsigmoid(z1[2]), fsigmoid(z1[3]));
;                         *(u32x4*)(G + (size_t)r * 2048 + gc + bj * 128) = w; } }
.LBB0_240:
	v_lshl_add_u64 v[168:169], v[166:167], 2, s[14:15]
	s_nop 1
	v_lshl_add_u32 v170, s95, 8, v178
	v_ashrrev_i32_e32 v171, 31, v170
	v_lshl_add_u64 v[128:129], v[170:171], 2, s[12:13]
	global_load_dwordx4 v[140:143], v[128:129], off
	global_load_dwordx4 v[136:139], v[128:129], off offset:16
	global_load_dwordx4 v[132:135], v[128:129], off offset:512
	s_nop 0
	global_load_dwordx4 v[128:131], v[128:129], off offset:528
	v_lshlrev_b64 v[172:173], 12, v[166:167]
	v_lshl_add_u64 v[186:187], s[26:27], 0, v[172:173]
	v_lshlrev_b64 v[172:173], 1, v[170:171]
	v_lshl_add_u64 v[170:171], v[186:187], 0, v[172:173]
	v_lshl_add_u64 v[188:189], v[164:165], 2, s[14:15]
	s_mov_b32 s49, 0x80000
	s_mov_b64 s[24:25], 0x80000
	s_waitcnt vmcnt(0)
	v_fmamk_f32 v184, v238, 0x3a800000, v182
	v_rsq_f32_e32 v184, v184
	s_nop 0
	v_pk_fma_f32 v[186:187], v[126:127], v[184:185], v[142:143] op_sel_hi:[1,0,1]
	v_pk_fma_f32 v[190:191], v[124:125], v[184:185], v[140:141] op_sel_hi:[1,0,1]
	v_pk_fma_f32 v[192:193], v[122:123], v[184:185], v[138:139] op_sel_hi:[1,0,1]
	v_pk_fma_f32 v[194:195], v[120:121], v[184:185], v[136:137] op_sel_hi:[1,0,1]
	v_pk_fma_f32 v[196:197], v[118:119], v[184:185], v[134:135] op_sel_hi:[1,0,1]
	v_pk_fma_f32 v[198:199], v[116:117], v[184:185], v[132:133] op_sel_hi:[1,0,1]
	v_pk_fma_f32 v[200:201], v[114:115], v[184:185], v[130:131] op_sel_hi:[1,0,1]
	v_pk_fma_f32 v[184:185], v[112:113], v[184:185], v[128:129] op_sel_hi:[1,0,1]
	v_mul_f32_e32 v186, 0xbfb8aa3b, v186
	v_mul_f32_e32 v187, 0xbfb8aa3b, v187
	v_mul_f32_e32 v190, 0xbfb8aa3b, v190
	v_mul_f32_e32 v191, 0xbfb8aa3b, v191
	v_mul_f32_e32 v194, 0xbfb8aa3b, v194
	v_mul_f32_e32 v195, 0xbfb8aa3b, v195
	v_mul_f32_e32 v192, 0xbfb8aa3b, v192
	v_mul_f32_e32 v193, 0xbfb8aa3b, v193
	v_mul_f32_e32 v184, 0xbfb8aa3b, v184
	v_mul_f32_e32 v185, 0xbfb8aa3b, v185
	v_exp_f32_e32 v186, v186
	v_exp_f32_e32 v187, v187
	v_mul_f32_e32 v198, 0xbfb8aa3b, v198
	v_mul_f32_e32 v199, 0xbfb8aa3b, v199
	v_mul_f32_e32 v196, 0xbfb8aa3b, v196
	v_mul_f32_e32 v197, 0xbfb8aa3b, v197
	v_mul_f32_e32 v200, 0xbfb8aa3b, v200
	v_mul_f32_e32 v201, 0xbfb8aa3b, v201
	v_exp_f32_e32 v190, v190
	v_exp_f32_e32 v191, v191
	v_exp_f32_e32 v194, v194
	v_exp_f32_e32 v195, v195
	v_exp_f32_e32 v192, v192
	v_exp_f32_e32 v193, v193
	v_exp_f32_e32 v184, v184
	v_exp_f32_e32 v185, v185
	v_exp_f32_e32 v198, v198
	v_exp_f32_e32 v199, v199
	v_exp_f32_e32 v196, v196
	v_exp_f32_e32 v197, v197
	v_exp_f32_e32 v200, v200
	v_exp_f32_e32 v201, v201
	v_add_f32_e32 v186, 1.0, v186
	v_add_f32_e32 v187, 1.0, v187
	v_add_f32_e32 v190, 1.0, v190
	v_add_f32_e32 v191, 1.0, v191
	v_add_f32_e32 v194, 1.0, v194
	v_add_f32_e32 v195, 1.0, v195
	v_add_f32_e32 v192, 1.0, v192
	v_add_f32_e32 v193, 1.0, v193
	v_add_f32_e32 v184, 1.0, v184
	v_add_f32_e32 v185, 1.0, v185
	v_rcp_f32_e32 v186, v186
	v_rcp_f32_e32 v187, v187
	v_add_f32_e32 v198, 1.0, v198
	v_add_f32_e32 v199, 1.0, v199
	v_add_f32_e32 v196, 1.0, v196
	v_add_f32_e32 v197, 1.0, v197
	v_add_f32_e32 v200, 1.0, v200
	v_add_f32_e32 v201, 1.0, v201
	v_rcp_f32_e32 v190, v190
	v_rcp_f32_e32 v191, v191
	v_rcp_f32_e32 v194, v194
	v_rcp_f32_e32 v195, v195
	v_rcp_f32_e32 v192, v192
	v_rcp_f32_e32 v193, v193
	v_rcp_f32_e32 v202, v184
	v_rcp_f32_e32 v203, v185
	v_cvt_pk_bf16_f32 v184, v190, v191
	v_cvt_pk_bf16_f32 v185, v186, v187
	v_cvt_pk_bf16_f32 v186, v194, v195
	v_cvt_pk_bf16_f32 v187, v192, v193
	v_rcp_f32_e32 v198, v198
	v_rcp_f32_e32 v199, v199
	v_rcp_f32_e32 v196, v196
	v_rcp_f32_e32 v197, v197
	v_rcp_f32_e32 v200, v200
	v_rcp_f32_e32 v201, v201
	global_store_dwordx4 v[170:171], v[184:187], off
	s_nop 1
	v_cvt_pk_bf16_f32 v184, v198, v199
	v_cvt_pk_bf16_f32 v185, v196, v197
	v_cvt_pk_bf16_f32 v186, v202, v203
	v_cvt_pk_bf16_f32 v187, v200, v201
	global_store_dwordx4 v[170:171], v[184:187], off offset:256
	s_nop 1
	v_lshl_add_u64 v[188:189], v[162:163], 2, s[14:15]
	v_lshlrev_b64 v[184:185], 12, v[164:165]
	v_lshl_add_u64 v[184:185], s[26:27], 0, v[184:185]
	v_lshl_add_u64 v[190:191], v[184:185], 0, v[172:173]
	s_nop 0
	v_fmamk_f32 v186, v239, 0x3a800000, v182
	v_rsq_f32_e32 v186, v186
	s_nop 0
	v_pk_fma_f32 v[184:185], v[110:111], v[186:187], v[142:143] op_sel_hi:[1,0,1]
	v_pk_fma_f32 v[192:193], v[108:109], v[186:187], v[140:141] op_sel_hi:[1,0,1]
	v_pk_fma_f32 v[194:195], v[106:107], v[186:187], v[138:139] op_sel_hi:[1,0,1]
	v_pk_fma_f32 v[196:197], v[104:105], v[186:187], v[136:137] op_sel_hi:[1,0,1]
	v_pk_fma_f32 v[198:199], v[102:103], v[186:187], v[134:135] op_sel_hi:[1,0,1]
	v_pk_fma_f32 v[200:201], v[100:101], v[186:187], v[132:133] op_sel_hi:[1,0,1]
	v_pk_fma_f32 v[202:203], v[98:99], v[186:187], v[130:131] op_sel_hi:[1,0,1]
	v_pk_fma_f32 v[186:187], v[96:97], v[186:187], v[128:129] op_sel_hi:[1,0,1]
	v_mul_f32_e32 v185, 0xbfb8aa3b, v185
	v_mul_f32_e32 v192, 0xbfb8aa3b, v192
	v_mul_f32_e32 v193, 0xbfb8aa3b, v193
	v_mul_f32_e32 v184, 0xbfb8aa3b, v184
	v_mul_f32_e32 v196, 0xbfb8aa3b, v196
	v_mul_f32_e32 v197, 0xbfb8aa3b, v197
	v_mul_f32_e32 v194, 0xbfb8aa3b, v194
	v_mul_f32_e32 v195, 0xbfb8aa3b, v195
	v_mul_f32_e32 v186, 0xbfb8aa3b, v186
	v_mul_f32_e32 v187, 0xbfb8aa3b, v187
	v_exp_f32_e32 v185, v185
	v_mul_f32_e32 v200, 0xbfb8aa3b, v200
	v_mul_f32_e32 v201, 0xbfb8aa3b, v201
	v_mul_f32_e32 v198, 0xbfb8aa3b, v198
	v_mul_f32_e32 v199, 0xbfb8aa3b, v199
	v_mul_f32_e32 v202, 0xbfb8aa3b, v202
	v_mul_f32_e32 v203, 0xbfb8aa3b, v203
	v_exp_f32_e32 v192, v192
	v_exp_f32_e32 v193, v193
	v_exp_f32_e32 v184, v184
	v_exp_f32_e32 v196, v196
	v_exp_f32_e32 v197, v197
	v_exp_f32_e32 v194, v194
	v_exp_f32_e32 v195, v195
	v_exp_f32_e32 v186, v186
	v_exp_f32_e32 v187, v187
	v_exp_f32_e32 v200, v200
	v_exp_f32_e32 v201, v201
; __device__ __forceinline__ unsigned pk2(float lo, float hi) { return pg8::cvt_pk_bf16(lo, hi); }
; __device__ __forceinline__ float fsigmoid(float z) { return __builtin_amdgcn_rcpf(1.0f + __builtin_amdgcn_exp2f(-LOG2E * z)); }
; __device__ __forceinline__ float rstd_of(float ssq) { return __builtin_amdgcn_rsqf(ssq * (1.0f / DM) + EPS); }
;     __device__ __forceinline__ void operator()(const f32x4 (&acc)[2][2][4][2], const Unit& u, int wr, int wc, int fr, int fq) const {
;     ...
;                 for (int m = 0; m < 4; ++m) { const int r = row0 + ai * 128 + m * 16; const float rs = rstd_of(ssq0[r]);
; #pragma unroll
;                     for (int bj = 0; bj < 2; ++bj) { const f32x4 z0 = acc[ai][bj][m][0] * rs + bv[bj][0], z1 = acc[ai][bj][m][1] * rs + bv[bj][1];
;                         u32x4 w; w.x = pk2(fsigmoid(z0[0]), fsigmoid(z0[1])); w.y = pk2(fsigmoid(z0[2]), fsigmoid(z0[3])); w.z = pk2(fsigmoid(z1[0]), fsigmoid(z1[1])); w.w = pk2(fsigmoid(z1[2]), fsigmoid(z1[3]));
;                         *(u32x4*)(G + (size_t)r * 2048 + gc + bj * 128) = w; } }
	v_exp_f32_e32 v198, v198
	v_exp_f32_e32 v199, v199
	v_exp_f32_e32 v202, v202
	v_exp_f32_e32 v203, v203
	v_add_f32_e32 v185, 1.0, v185
	v_add_f32_e32 v192, 1.0, v192
	v_add_f32_e32 v193, 1.0, v193
	v_add_f32_e32 v184, 1.0, v184
	v_add_f32_e32 v196, 1.0, v196
	v_add_f32_e32 v197, 1.0, v197
	v_add_f32_e32 v194, 1.0, v194
	v_add_f32_e32 v195, 1.0, v195
	v_add_f32_e32 v186, 1.0, v186
	v_add_f32_e32 v187, 1.0, v187
	v_rcp_f32_e32 v185, v185
	v_add_f32_e32 v200, 1.0, v200
	v_add_f32_e32 v201, 1.0, v201
	v_add_f32_e32 v198, 1.0, v198
	v_add_f32_e32 v199, 1.0, v199
	v_add_f32_e32 v202, 1.0, v202
	v_add_f32_e32 v203, 1.0, v203
	v_rcp_f32_e32 v192, v192
	v_rcp_f32_e32 v193, v193
	v_rcp_f32_e32 v204, v184
	v_rcp_f32_e32 v196, v196
	v_rcp_f32_e32 v197, v197
	v_rcp_f32_e32 v194, v194
	v_rcp_f32_e32 v195, v195
	v_rcp_f32_e32 v205, v186
	v_rcp_f32_e32 v206, v187
	v_cvt_pk_bf16_f32 v184, v192, v193
	v_cvt_pk_bf16_f32 v185, v204, v185
	v_cvt_pk_bf16_f32 v186, v196, v197
	v_cvt_pk_bf16_f32 v187, v194, v195
	v_rcp_f32_e32 v200, v200
	v_rcp_f32_e32 v201, v201
	v_rcp_f32_e32 v198, v198
	v_rcp_f32_e32 v199, v199
	v_rcp_f32_e32 v202, v202
	v_rcp_f32_e32 v203, v203
	global_store_dwordx4 v[190:191], v[184:187], off
	s_nop 1
	v_cvt_pk_bf16_f32 v184, v200, v201
	v_cvt_pk_bf16_f32 v185, v198, v199
	v_cvt_pk_bf16_f32 v186, v205, v206
	v_cvt_pk_bf16_f32 v187, v202, v203
	global_store_dwordx4 v[190:191], v[184:187], off offset:256
	s_nop 1
	v_lshl_add_u64 v[188:189], v[160:161], 2, s[14:15]
	v_lshlrev_b64 v[184:185], 12, v[162:163]
	v_lshl_add_u64 v[184:185], s[26:27], 0, v[184:185]
	v_lshl_add_u64 v[190:191], v[184:185], 0, v[172:173]
	s_nop 0
	v_fmamk_f32 v186, v240, 0x3a800000, v182
	v_rsq_f32_e32 v186, v186
	s_nop 0
	v_pk_fma_f32 v[184:185], v[94:95], v[186:187], v[142:143] op_sel_hi:[1,0,1]
	v_pk_fma_f32 v[192:193], v[92:93], v[186:187], v[140:141] op_sel_hi:[1,0,1]
	v_pk_fma_f32 v[194:195], v[90:91], v[186:187], v[138:139] op_sel_hi:[1,0,1]
	v_pk_fma_f32 v[196:197], v[88:89], v[186:187], v[136:137] op_sel_hi:[1,0,1]
	v_pk_fma_f32 v[198:199], v[82:83], v[186:187], v[134:135] op_sel_hi:[1,0,1]
	v_pk_fma_f32 v[200:201], v[80:81], v[186:187], v[132:133] op_sel_hi:[1,0,1]
	v_pk_fma_f32 v[202:203], v[78:79], v[186:187], v[130:131] op_sel_hi:[1,0,1]
	v_pk_fma_f32 v[186:187], v[76:77], v[186:187], v[128:129] op_sel_hi:[1,0,1]
	v_mul_f32_e32 v185, 0xbfb8aa3b, v185
	v_mul_f32_e32 v192, 0xbfb8aa3b, v192
	v_mul_f32_e32 v193, 0xbfb8aa3b, v193
	v_mul_f32_e32 v184, 0xbfb8aa3b, v184
	v_mul_f32_e32 v196, 0xbfb8aa3b, v196
	v_mul_f32_e32 v197, 0xbfb8aa3b, v197
	v_mul_f32_e32 v194, 0xbfb8aa3b, v194
	v_mul_f32_e32 v195, 0xbfb8aa3b, v195
	v_mul_f32_e32 v186, 0xbfb8aa3b, v186
	v_mul_f32_e32 v187, 0xbfb8aa3b, v187
	v_exp_f32_e32 v185, v185
	v_mul_f32_e32 v200, 0xbfb8aa3b, v200
	v_mul_f32_e32 v201, 0xbfb8aa3b, v201
	v_mul_f32_e32 v198, 0xbfb8aa3b, v198
	v_mul_f32_e32 v199, 0xbfb8aa3b, v199
	v_mul_f32_e32 v202, 0xbfb8aa3b, v202
	v_mul_f32_e32 v203, 0xbfb8aa3b, v203
	v_exp_f32_e32 v192, v192
	v_exp_f32_e32 v193, v193
	v_exp_f32_e32 v184, v184
	v_exp_f32_e32 v196, v196
	v_exp_f32_e32 v197, v197
	v_exp_f32_e32 v194, v194
	v_exp_f32_e32 v195, v195
	v_exp_f32_e32 v186, v186
	v_exp_f32_e32 v187, v187
	v_exp_f32_e32 v200, v200
	v_exp_f32_e32 v201, v201
	v_exp_f32_e32 v198, v198
	v_exp_f32_e32 v199, v199
	v_exp_f32_e32 v202, v202
	v_exp_f32_e32 v203, v203
	v_add_f32_e32 v185, 1.0, v185
	v_add_f32_e32 v192, 1.0, v192
	v_add_f32_e32 v193, 1.0, v193
	v_add_f32_e32 v184, 1.0, v184
	v_add_f32_e32 v196, 1.0, v196
	v_add_f32_e32 v197, 1.0, v197
	v_add_f32_e32 v194, 1.0, v194
	v_add_f32_e32 v195, 1.0, v195
	v_add_f32_e32 v186, 1.0, v186
	v_add_f32_e32 v187, 1.0, v187
	v_rcp_f32_e32 v185, v185
	v_add_f32_e32 v200, 1.0, v200
	v_add_f32_e32 v201, 1.0, v201
	v_add_f32_e32 v198, 1.0, v198
	v_add_f32_e32 v199, 1.0, v199
	v_add_f32_e32 v202, 1.0, v202
	v_add_f32_e32 v203, 1.0, v203
	v_rcp_f32_e32 v192, v192
	v_rcp_f32_e32 v193, v193
	v_rcp_f32_e32 v204, v184
	v_rcp_f32_e32 v196, v196
	v_rcp_f32_e32 v197, v197
	v_rcp_f32_e32 v194, v194
	v_rcp_f32_e32 v195, v195
	v_rcp_f32_e32 v205, v186
	v_rcp_f32_e32 v206, v187
	v_cvt_pk_bf16_f32 v184, v192, v193
	v_cvt_pk_bf16_f32 v185, v204, v185
	v_cvt_pk_bf16_f32 v186, v196, v197
	v_cvt_pk_bf16_f32 v187, v194, v195
	v_rcp_f32_e32 v200, v200
	v_rcp_f32_e32 v201, v201
	v_rcp_f32_e32 v198, v198
	v_rcp_f32_e32 v199, v199
	v_rcp_f32_e32 v202, v202
	v_rcp_f32_e32 v203, v203
	global_store_dwordx4 v[190:191], v[184:187], off
	s_nop 1
	v_cvt_pk_bf16_f32 v184, v200, v201
	v_cvt_pk_bf16_f32 v185, v198, v199
	v_cvt_pk_bf16_f32 v186, v205, v206
	v_cvt_pk_bf16_f32 v187, v202, v203
	global_store_dwordx4 v[190:191], v[184:187], off offset:256
	s_nop 1
	s_nop 0
	v_lshlrev_b64 v[186:187], 12, v[160:161]
	v_lshl_add_u64 v[186:187], s[26:27], 0, v[186:187]
	v_lshl_add_u64 v[172:173], v[186:187], 0, v[172:173]
	s_nop 0
	v_fmamk_f32 v184, v241, 0x3a800000, v182
	v_rsq_f32_e32 v184, v184
	s_nop 0
	v_pk_fma_f32 v[186:187], v[86:87], v[184:185], v[142:143] op_sel_hi:[1,0,1]
	v_pk_fma_f32 v[188:189], v[84:85], v[184:185], v[140:141] op_sel_hi:[1,0,1]
	v_pk_fma_f32 v[190:191], v[74:75], v[184:185], v[138:139] op_sel_hi:[1,0,1]
	v_pk_fma_f32 v[192:193], v[72:73], v[184:185], v[136:137] op_sel_hi:[1,0,1]
	v_pk_fma_f32 v[194:195], v[70:71], v[184:185], v[134:135] op_sel_hi:[1,0,1]
	v_pk_fma_f32 v[196:197], v[68:69], v[184:185], v[132:133] op_sel_hi:[1,0,1]
	v_pk_fma_f32 v[198:199], v[66:67], v[184:185], v[130:131] op_sel_hi:[1,0,1]
	v_pk_fma_f32 v[184:185], v[64:65], v[184:185], v[128:129] op_sel_hi:[1,0,1]
	v_mul_f32_e32 v186, 0xbfb8aa3b, v186
	v_mul_f32_e32 v187, 0xbfb8aa3b, v187
; __device__ __forceinline__ unsigned pk2(float lo, float hi) { return pg8::cvt_pk_bf16(lo, hi); }
; __device__ __forceinline__ float fsigmoid(float z) { return __builtin_amdgcn_rcpf(1.0f + __builtin_amdgcn_exp2f(-LOG2E * z)); }
; __device__ __forceinline__ float rstd_of(float ssq) { return __builtin_amdgcn_rsqf(ssq * (1.0f / DM) + EPS); }
;     __device__ __forceinline__ void operator()(const f32x4 (&acc)[2][2][4][2], const Unit& u, int wr, int wc, int fr, int fq) const {
;     ...
;                 for (int m = 0; m < 4; ++m) { const int r = row0 + ai * 128 + m * 16; const float rs = rstd_of(ssq0[r]);
; #pragma unroll
;                     for (int bj = 0; bj < 2; ++bj) { const f32x4 z0 = acc[ai][bj][m][0] * rs + bv[bj][0], z1 = acc[ai][bj][m][1] * rs + bv[bj][1];
;                         u32x4 w; w.x = pk2(fsigmoid(z0[0]), fsigmoid(z0[1])); w.y = pk2(fsigmoid(z0[2]), fsigmoid(z0[3])); w.z = pk2(fsigmoid(z1[0]), fsigmoid(z1[1])); w.w = pk2(fsigmoid(z1[2]), fsigmoid(z1[3]));
;                         *(u32x4*)(G + (size_t)r * 2048 + gc + bj * 128) = w; } }
	v_mul_f32_e32 v188, 0xbfb8aa3b, v188
	v_mul_f32_e32 v189, 0xbfb8aa3b, v189
	v_mul_f32_e32 v192, 0xbfb8aa3b, v192
	v_mul_f32_e32 v193, 0xbfb8aa3b, v193
	v_mul_f32_e32 v190, 0xbfb8aa3b, v190
	v_mul_f32_e32 v191, 0xbfb8aa3b, v191
	v_mul_f32_e32 v184, 0xbfb8aa3b, v184
	v_mul_f32_e32 v185, 0xbfb8aa3b, v185
	v_exp_f32_e32 v186, v186
	v_exp_f32_e32 v187, v187
	v_mul_f32_e32 v196, 0xbfb8aa3b, v196
	v_mul_f32_e32 v197, 0xbfb8aa3b, v197
	v_mul_f32_e32 v194, 0xbfb8aa3b, v194
	v_mul_f32_e32 v195, 0xbfb8aa3b, v195
	v_mul_f32_e32 v198, 0xbfb8aa3b, v198
	v_mul_f32_e32 v199, 0xbfb8aa3b, v199
	v_exp_f32_e32 v188, v188
	v_exp_f32_e32 v189, v189
	v_exp_f32_e32 v192, v192
	v_exp_f32_e32 v193, v193
	v_exp_f32_e32 v190, v190
	v_exp_f32_e32 v191, v191
	v_exp_f32_e32 v184, v184
	v_exp_f32_e32 v185, v185
	v_exp_f32_e32 v196, v196
	v_exp_f32_e32 v197, v197
	v_exp_f32_e32 v194, v194
	v_exp_f32_e32 v195, v195
	v_exp_f32_e32 v198, v198
	v_exp_f32_e32 v199, v199
	v_add_f32_e32 v186, 1.0, v186
	v_add_f32_e32 v187, 1.0, v187
	v_add_f32_e32 v188, 1.0, v188
	v_add_f32_e32 v189, 1.0, v189
	v_add_f32_e32 v192, 1.0, v192
	v_add_f32_e32 v193, 1.0, v193
	v_add_f32_e32 v190, 1.0, v190
	v_add_f32_e32 v191, 1.0, v191
	v_add_f32_e32 v184, 1.0, v184
	v_add_f32_e32 v185, 1.0, v185
	v_rcp_f32_e32 v186, v186
	v_rcp_f32_e32 v187, v187
	v_add_f32_e32 v196, 1.0, v196
	v_add_f32_e32 v197, 1.0, v197
	v_add_f32_e32 v194, 1.0, v194
	v_add_f32_e32 v195, 1.0, v195
	v_add_f32_e32 v198, 1.0, v198
	v_add_f32_e32 v199, 1.0, v199
	v_rcp_f32_e32 v188, v188
	v_rcp_f32_e32 v189, v189
	v_rcp_f32_e32 v192, v192
	v_rcp_f32_e32 v193, v193
	v_rcp_f32_e32 v190, v190
	v_rcp_f32_e32 v191, v191
	v_rcp_f32_e32 v200, v184
	v_rcp_f32_e32 v201, v185
	v_cvt_pk_bf16_f32 v184, v188, v189
	v_cvt_pk_bf16_f32 v185, v186, v187
	v_cvt_pk_bf16_f32 v186, v192, v193
	v_cvt_pk_bf16_f32 v187, v190, v191
	v_rcp_f32_e32 v196, v196
	v_rcp_f32_e32 v197, v197
	v_rcp_f32_e32 v194, v194
	v_rcp_f32_e32 v195, v195
	v_rcp_f32_e32 v198, v198
	v_rcp_f32_e32 v199, v199
	global_store_dwordx4 v[172:173], v[184:187], off
	v_add_co_u32_e32 v188, vcc, s49, v170
	s_nop 0
	v_cvt_pk_bf16_f32 v184, v196, v197
	v_cvt_pk_bf16_f32 v185, v194, v195
	v_cvt_pk_bf16_f32 v186, v200, v201
	v_cvt_pk_bf16_f32 v187, v198, v199
	global_store_dwordx4 v[172:173], v[184:187], off offset:256
	s_nop 1
	v_lshl_add_u64 v[172:173], v[170:171], 0, s[24:25]
	v_addc_co_u32_e32 v189, vcc, 0, v171, vcc
	s_mov_b32 s49, 0x90000
	s_mov_b64 s[24:25], 0x90000
	s_nop 0
	v_fmamk_f32 v184, v242, 0x3a800000, v182
	v_rsq_f32_e32 v184, v184
	s_nop 0
	v_pk_fma_f32 v[186:187], v[62:63], v[184:185], v[142:143] op_sel_hi:[1,0,1]
	v_pk_fma_f32 v[190:191], v[60:61], v[184:185], v[140:141] op_sel_hi:[1,0,1]
	v_pk_fma_f32 v[192:193], v[58:59], v[184:185], v[138:139] op_sel_hi:[1,0,1]
	v_pk_fma_f32 v[194:195], v[56:57], v[184:185], v[136:137] op_sel_hi:[1,0,1]
	v_pk_fma_f32 v[196:197], v[54:55], v[184:185], v[134:135] op_sel_hi:[1,0,1]
	v_pk_fma_f32 v[198:199], v[52:53], v[184:185], v[132:133] op_sel_hi:[1,0,1]
	v_pk_fma_f32 v[200:201], v[50:51], v[184:185], v[130:131] op_sel_hi:[1,0,1]
	v_pk_fma_f32 v[184:185], v[48:49], v[184:185], v[128:129] op_sel_hi:[1,0,1]
	v_mul_f32_e32 v186, 0xbfb8aa3b, v186
	v_mul_f32_e32 v187, 0xbfb8aa3b, v187
	v_mul_f32_e32 v190, 0xbfb8aa3b, v190
	v_mul_f32_e32 v191, 0xbfb8aa3b, v191
	v_mul_f32_e32 v194, 0xbfb8aa3b, v194
	v_mul_f32_e32 v195, 0xbfb8aa3b, v195
	v_mul_f32_e32 v192, 0xbfb8aa3b, v192
	v_mul_f32_e32 v193, 0xbfb8aa3b, v193
	v_mul_f32_e32 v184, 0xbfb8aa3b, v184
	v_mul_f32_e32 v185, 0xbfb8aa3b, v185
	v_exp_f32_e32 v186, v186
	v_exp_f32_e32 v187, v187
	v_mul_f32_e32 v198, 0xbfb8aa3b, v198
	v_mul_f32_e32 v199, 0xbfb8aa3b, v199
	v_mul_f32_e32 v196, 0xbfb8aa3b, v196
	v_mul_f32_e32 v197, 0xbfb8aa3b, v197
	v_mul_f32_e32 v200, 0xbfb8aa3b, v200
	v_mul_f32_e32 v201, 0xbfb8aa3b, v201
	v_exp_f32_e32 v190, v190
	v_exp_f32_e32 v191, v191
	v_exp_f32_e32 v194, v194
	v_exp_f32_e32 v195, v195
	v_exp_f32_e32 v192, v192
	v_exp_f32_e32 v193, v193
	v_exp_f32_e32 v184, v184
	v_exp_f32_e32 v185, v185
	v_exp_f32_e32 v198, v198
	v_exp_f32_e32 v199, v199
	v_exp_f32_e32 v196, v196
	v_exp_f32_e32 v197, v197
	v_exp_f32_e32 v200, v200
	v_exp_f32_e32 v201, v201
	v_add_f32_e32 v186, 1.0, v186
	v_add_f32_e32 v187, 1.0, v187
	v_add_f32_e32 v190, 1.0, v190
	v_add_f32_e32 v191, 1.0, v191
	v_add_f32_e32 v194, 1.0, v194
	v_add_f32_e32 v195, 1.0, v195
	v_add_f32_e32 v192, 1.0, v192
	v_add_f32_e32 v193, 1.0, v193
	v_add_f32_e32 v184, 1.0, v184
	v_add_f32_e32 v185, 1.0, v185
	v_rcp_f32_e32 v186, v186
	v_rcp_f32_e32 v187, v187
	v_add_f32_e32 v198, 1.0, v198
	v_add_f32_e32 v199, 1.0, v199
	v_add_f32_e32 v196, 1.0, v196
	v_add_f32_e32 v197, 1.0, v197
	v_add_f32_e32 v200, 1.0, v200
	v_add_f32_e32 v201, 1.0, v201
	v_rcp_f32_e32 v190, v190
	v_rcp_f32_e32 v191, v191
	v_rcp_f32_e32 v194, v194
	v_rcp_f32_e32 v195, v195
	v_rcp_f32_e32 v192, v192
	v_rcp_f32_e32 v193, v193
	v_rcp_f32_e32 v202, v184
	v_rcp_f32_e32 v203, v185
	v_cvt_pk_bf16_f32 v184, v190, v191
	v_cvt_pk_bf16_f32 v185, v186, v187
	v_cvt_pk_bf16_f32 v186, v194, v195
	v_cvt_pk_bf16_f32 v187, v192, v193
	v_rcp_f32_e32 v198, v198
	v_rcp_f32_e32 v199, v199
	v_rcp_f32_e32 v196, v196
	v_rcp_f32_e32 v197, v197
	v_rcp_f32_e32 v200, v200
	v_rcp_f32_e32 v201, v201
	global_store_dwordx4 v[188:189], v[184:187], off
	v_add_co_u32_e32 v188, vcc, s49, v170
	s_nop 0
	v_cvt_pk_bf16_f32 v184, v198, v199
	v_cvt_pk_bf16_f32 v185, v196, v197
	v_cvt_pk_bf16_f32 v186, v202, v203
	v_cvt_pk_bf16_f32 v187, v200, v201
	global_store_dwordx4 v[172:173], v[184:187], off offset:256
	s_nop 1
	v_lshl_add_u64 v[172:173], v[170:171], 0, s[24:25]
	v_addc_co_u32_e32 v189, vcc, 0, v171, vcc
; __device__ __forceinline__ unsigned pk2(float lo, float hi) { return pg8::cvt_pk_bf16(lo, hi); }
; __device__ __forceinline__ float fsigmoid(float z) { return __builtin_amdgcn_rcpf(1.0f + __builtin_amdgcn_exp2f(-LOG2E * z)); }
; __device__ __forceinline__ float rstd_of(float ssq) { return __builtin_amdgcn_rsqf(ssq * (1.0f / DM) + EPS); }
;     __device__ __forceinline__ void operator()(const f32x4 (&acc)[2][2][4][2], const Unit& u, int wr, int wc, int fr, int fq) const {
;     ...
;                 for (int m = 0; m < 4; ++m) { const int r = row0 + ai * 128 + m * 16; const float rs = rstd_of(ssq0[r]);
; #pragma unroll
;                     for (int bj = 0; bj < 2; ++bj) { const f32x4 z0 = acc[ai][bj][m][0] * rs + bv[bj][0], z1 = acc[ai][bj][m][1] * rs + bv[bj][1];
;                         u32x4 w; w.x = pk2(fsigmoid(z0[0]), fsigmoid(z0[1])); w.y = pk2(fsigmoid(z0[2]), fsigmoid(z0[3])); w.z = pk2(fsigmoid(z1[0]), fsigmoid(z1[1])); w.w = pk2(fsigmoid(z1[2]), fsigmoid(z1[3]));
;                         *(u32x4*)(G + (size_t)r * 2048 + gc + bj * 128) = w; } }
	s_mov_b32 s49, 0xa0000
	s_mov_b64 s[24:25], 0xa0000
	s_nop 0
	v_fmamk_f32 v184, v243, 0x3a800000, v182
	v_rsq_f32_e32 v184, v184
	s_nop 0
	v_pk_fma_f32 v[186:187], v[46:47], v[184:185], v[142:143] op_sel_hi:[1,0,1]
	v_pk_fma_f32 v[190:191], v[44:45], v[184:185], v[140:141] op_sel_hi:[1,0,1]
	v_pk_fma_f32 v[192:193], v[42:43], v[184:185], v[138:139] op_sel_hi:[1,0,1]
	v_pk_fma_f32 v[194:195], v[40:41], v[184:185], v[136:137] op_sel_hi:[1,0,1]
	v_pk_fma_f32 v[196:197], v[38:39], v[184:185], v[134:135] op_sel_hi:[1,0,1]
	v_pk_fma_f32 v[198:199], v[36:37], v[184:185], v[132:133] op_sel_hi:[1,0,1]
	v_pk_fma_f32 v[200:201], v[34:35], v[184:185], v[130:131] op_sel_hi:[1,0,1]
	v_pk_fma_f32 v[184:185], v[32:33], v[184:185], v[128:129] op_sel_hi:[1,0,1]
	v_mul_f32_e32 v186, 0xbfb8aa3b, v186
	v_mul_f32_e32 v187, 0xbfb8aa3b, v187
	v_mul_f32_e32 v190, 0xbfb8aa3b, v190
	v_mul_f32_e32 v191, 0xbfb8aa3b, v191
	v_mul_f32_e32 v194, 0xbfb8aa3b, v194
	v_mul_f32_e32 v195, 0xbfb8aa3b, v195
	v_mul_f32_e32 v192, 0xbfb8aa3b, v192
	v_mul_f32_e32 v193, 0xbfb8aa3b, v193
	v_mul_f32_e32 v184, 0xbfb8aa3b, v184
	v_mul_f32_e32 v185, 0xbfb8aa3b, v185
	v_exp_f32_e32 v186, v186
	v_exp_f32_e32 v187, v187
	v_mul_f32_e32 v198, 0xbfb8aa3b, v198
	v_mul_f32_e32 v199, 0xbfb8aa3b, v199
	v_mul_f32_e32 v196, 0xbfb8aa3b, v196
	v_mul_f32_e32 v197, 0xbfb8aa3b, v197
	v_mul_f32_e32 v200, 0xbfb8aa3b, v200
	v_mul_f32_e32 v201, 0xbfb8aa3b, v201
	v_exp_f32_e32 v190, v190
	v_exp_f32_e32 v191, v191
	v_exp_f32_e32 v194, v194
	v_exp_f32_e32 v195, v195
	v_exp_f32_e32 v192, v192
	v_exp_f32_e32 v193, v193
	v_exp_f32_e32 v184, v184
	v_exp_f32_e32 v185, v185
	v_exp_f32_e32 v198, v198
	v_exp_f32_e32 v199, v199
	v_exp_f32_e32 v196, v196
	v_exp_f32_e32 v197, v197
	v_exp_f32_e32 v200, v200
	v_exp_f32_e32 v201, v201
	v_add_f32_e32 v186, 1.0, v186
	v_add_f32_e32 v187, 1.0, v187
	v_add_f32_e32 v190, 1.0, v190
	v_add_f32_e32 v191, 1.0, v191
	v_add_f32_e32 v194, 1.0, v194
	v_add_f32_e32 v195, 1.0, v195
	v_add_f32_e32 v192, 1.0, v192
	v_add_f32_e32 v193, 1.0, v193
	v_add_f32_e32 v184, 1.0, v184
	v_add_f32_e32 v185, 1.0, v185
	v_rcp_f32_e32 v186, v186
	v_rcp_f32_e32 v187, v187
	v_add_f32_e32 v198, 1.0, v198
	v_add_f32_e32 v199, 1.0, v199
	v_add_f32_e32 v196, 1.0, v196
	v_add_f32_e32 v197, 1.0, v197
	v_add_f32_e32 v200, 1.0, v200
	v_add_f32_e32 v201, 1.0, v201
	v_rcp_f32_e32 v190, v190
	v_rcp_f32_e32 v191, v191
	v_rcp_f32_e32 v194, v194
	v_rcp_f32_e32 v195, v195
	v_rcp_f32_e32 v192, v192
	v_rcp_f32_e32 v193, v193
	v_rcp_f32_e32 v202, v184
	v_rcp_f32_e32 v203, v185
	v_cvt_pk_bf16_f32 v184, v190, v191
	v_cvt_pk_bf16_f32 v185, v186, v187
	v_cvt_pk_bf16_f32 v186, v194, v195
	v_cvt_pk_bf16_f32 v187, v192, v193
	v_rcp_f32_e32 v198, v198
	v_rcp_f32_e32 v199, v199
	v_rcp_f32_e32 v196, v196
	v_rcp_f32_e32 v197, v197
	v_rcp_f32_e32 v200, v200
	v_rcp_f32_e32 v201, v201
	global_store_dwordx4 v[188:189], v[184:187], off
	v_add_co_u32_e32 v188, vcc, s49, v170
	s_nop 0
	v_cvt_pk_bf16_f32 v184, v198, v199
	v_cvt_pk_bf16_f32 v185, v196, v197
	v_cvt_pk_bf16_f32 v186, v202, v203
	v_cvt_pk_bf16_f32 v187, v200, v201
	global_store_dwordx4 v[172:173], v[184:187], off offset:256
	s_nop 1
	v_lshl_add_u64 v[172:173], v[170:171], 0, s[24:25]
	v_addc_co_u32_e32 v189, vcc, 0, v171, vcc
	s_mov_b64 s[24:25], 0xb0000
	s_nop 0
	v_fmamk_f32 v184, v244, 0x3a800000, v182
	v_rsq_f32_e32 v184, v184
	s_nop 0
	v_pk_fma_f32 v[186:187], v[30:31], v[184:185], v[142:143] op_sel_hi:[1,0,1]
	v_pk_fma_f32 v[190:191], v[28:29], v[184:185], v[140:141] op_sel_hi:[1,0,1]
	v_pk_fma_f32 v[192:193], v[26:27], v[184:185], v[138:139] op_sel_hi:[1,0,1]
	v_pk_fma_f32 v[194:195], v[24:25], v[184:185], v[136:137] op_sel_hi:[1,0,1]
	v_pk_fma_f32 v[196:197], v[22:23], v[184:185], v[134:135] op_sel_hi:[1,0,1]
	v_pk_fma_f32 v[198:199], v[20:21], v[184:185], v[132:133] op_sel_hi:[1,0,1]
	v_pk_fma_f32 v[200:201], v[18:19], v[184:185], v[130:131] op_sel_hi:[1,0,1]
	v_pk_fma_f32 v[184:185], v[16:17], v[184:185], v[128:129] op_sel_hi:[1,0,1]
	v_mul_f32_e32 v186, 0xbfb8aa3b, v186
	v_mul_f32_e32 v187, 0xbfb8aa3b, v187
	v_mul_f32_e32 v190, 0xbfb8aa3b, v190
	v_mul_f32_e32 v191, 0xbfb8aa3b, v191
	v_mul_f32_e32 v194, 0xbfb8aa3b, v194
	v_mul_f32_e32 v195, 0xbfb8aa3b, v195
	v_mul_f32_e32 v192, 0xbfb8aa3b, v192
	v_mul_f32_e32 v193, 0xbfb8aa3b, v193
	v_mul_f32_e32 v184, 0xbfb8aa3b, v184
	v_mul_f32_e32 v185, 0xbfb8aa3b, v185
	v_exp_f32_e32 v186, v186
	v_exp_f32_e32 v187, v187
	v_mul_f32_e32 v198, 0xbfb8aa3b, v198
	v_mul_f32_e32 v199, 0xbfb8aa3b, v199
	v_mul_f32_e32 v196, 0xbfb8aa3b, v196
	v_mul_f32_e32 v197, 0xbfb8aa3b, v197
	v_mul_f32_e32 v200, 0xbfb8aa3b, v200
	v_mul_f32_e32 v201, 0xbfb8aa3b, v201
	v_exp_f32_e32 v190, v190
	v_exp_f32_e32 v191, v191
	v_exp_f32_e32 v194, v194
	v_exp_f32_e32 v195, v195
; __device__ __forceinline__ unsigned pk2(float lo, float hi) { return pg8::cvt_pk_bf16(lo, hi); }
; __device__ __forceinline__ float fsigmoid(float z) { return __builtin_amdgcn_rcpf(1.0f + __builtin_amdgcn_exp2f(-LOG2E * z)); }
; __device__ __forceinline__ float rstd_of(float ssq) { return __builtin_amdgcn_rsqf(ssq * (1.0f / DM) + EPS); }
;     __device__ __forceinline__ void operator()(const f32x4 (&acc)[2][2][4][2], const Unit& u, int wr, int wc, int fr, int fq) const {
;     ...
;                 for (int m = 0; m < 4; ++m) { const int r = row0 + ai * 128 + m * 16; const float rs = rstd_of(ssq0[r]);
; #pragma unroll
;                     for (int bj = 0; bj < 2; ++bj) { const f32x4 z0 = acc[ai][bj][m][0] * rs + bv[bj][0], z1 = acc[ai][bj][m][1] * rs + bv[bj][1];
;                         u32x4 w; w.x = pk2(fsigmoid(z0[0]), fsigmoid(z0[1])); w.y = pk2(fsigmoid(z0[2]), fsigmoid(z0[3])); w.z = pk2(fsigmoid(z1[0]), fsigmoid(z1[1])); w.w = pk2(fsigmoid(z1[2]), fsigmoid(z1[3]));
;                         *(u32x4*)(G + (size_t)r * 2048 + gc + bj * 128) = w; } }
	v_exp_f32_e32 v192, v192
	v_exp_f32_e32 v193, v193
	v_exp_f32_e32 v184, v184
	v_exp_f32_e32 v185, v185
	v_exp_f32_e32 v198, v198
	v_exp_f32_e32 v199, v199
	v_exp_f32_e32 v196, v196
	v_exp_f32_e32 v197, v197
	v_exp_f32_e32 v200, v200
	v_exp_f32_e32 v201, v201
	v_add_f32_e32 v186, 1.0, v186
	v_add_f32_e32 v187, 1.0, v187
	v_add_f32_e32 v190, 1.0, v190
	v_add_f32_e32 v191, 1.0, v191
	v_add_f32_e32 v194, 1.0, v194
	v_add_f32_e32 v195, 1.0, v195
	v_add_f32_e32 v192, 1.0, v192
	v_add_f32_e32 v193, 1.0, v193
	v_add_f32_e32 v184, 1.0, v184
	v_add_f32_e32 v185, 1.0, v185
	v_rcp_f32_e32 v186, v186
	v_rcp_f32_e32 v187, v187
	v_add_f32_e32 v198, 1.0, v198
	v_add_f32_e32 v199, 1.0, v199
	v_add_f32_e32 v196, 1.0, v196
	v_add_f32_e32 v197, 1.0, v197
	v_add_f32_e32 v200, 1.0, v200
	v_add_f32_e32 v201, 1.0, v201
	v_rcp_f32_e32 v190, v190
	v_rcp_f32_e32 v191, v191
	v_rcp_f32_e32 v194, v194
	v_rcp_f32_e32 v195, v195
	v_rcp_f32_e32 v192, v192
	v_rcp_f32_e32 v193, v193
	v_rcp_f32_e32 v202, v184
	v_rcp_f32_e32 v203, v185
	v_cvt_pk_bf16_f32 v184, v190, v191
	v_cvt_pk_bf16_f32 v185, v186, v187
	v_cvt_pk_bf16_f32 v186, v194, v195
	v_cvt_pk_bf16_f32 v187, v192, v193
	v_rcp_f32_e32 v198, v198
	v_rcp_f32_e32 v199, v199
	v_rcp_f32_e32 v196, v196
	v_rcp_f32_e32 v197, v197
	v_rcp_f32_e32 v200, v200
	v_rcp_f32_e32 v201, v201
	global_store_dwordx4 v[188:189], v[184:187], off
	s_nop 1
	v_cvt_pk_bf16_f32 v184, v198, v199
	v_cvt_pk_bf16_f32 v185, v196, v197
	v_cvt_pk_bf16_f32 v186, v202, v203
	v_cvt_pk_bf16_f32 v187, v200, v201
	global_store_dwordx4 v[172:173], v[184:187], off offset:256
	s_nop 1
	v_lshl_add_u64 v[168:169], v[170:171], 0, s[24:25]
	v_add_co_u32_e32 v170, vcc, s90, v170
	s_nop 0
	v_fmamk_f32 v172, v245, 0x3a800000, v182
	v_rsq_f32_e32 v172, v172
	v_addc_co_u32_e32 v171, vcc, 0, v171, vcc
	v_pk_fma_f32 v[142:143], v[14:15], v[172:173], v[142:143] op_sel_hi:[1,0,1]
	v_pk_fma_f32 v[140:141], v[12:13], v[172:173], v[140:141] op_sel_hi:[1,0,1]
	v_pk_fma_f32 v[138:139], v[10:11], v[172:173], v[138:139] op_sel_hi:[1,0,1]
	v_pk_fma_f32 v[136:137], v[8:9], v[172:173], v[136:137] op_sel_hi:[1,0,1]
	v_pk_fma_f32 v[130:131], v[2:3], v[172:173], v[130:131] op_sel_hi:[1,0,1]
	v_pk_fma_f32 v[128:129], v[0:1], v[172:173], v[128:129] op_sel_hi:[1,0,1]
	v_pk_fma_f32 v[134:135], v[6:7], v[172:173], v[134:135] op_sel_hi:[1,0,1]
	v_pk_fma_f32 v[132:133], v[4:5], v[172:173], v[132:133] op_sel_hi:[1,0,1]
	v_mul_f32_e32 v140, 0xbfb8aa3b, v140
	v_mul_f32_e32 v141, 0xbfb8aa3b, v141
	v_mul_f32_e32 v142, 0xbfb8aa3b, v142
	v_mul_f32_e32 v143, 0xbfb8aa3b, v143
	v_mul_f32_e32 v136, 0xbfb8aa3b, v136
	v_mul_f32_e32 v137, 0xbfb8aa3b, v137
	v_mul_f32_e32 v138, 0xbfb8aa3b, v138
	v_mul_f32_e32 v139, 0xbfb8aa3b, v139
	v_mul_f32_e32 v128, 0xbfb8aa3b, v128
	v_mul_f32_e32 v129, 0xbfb8aa3b, v129
	v_mul_f32_e32 v130, 0xbfb8aa3b, v130
	v_mul_f32_e32 v131, 0xbfb8aa3b, v131
	v_mul_f32_e32 v132, 0xbfb8aa3b, v132
	v_mul_f32_e32 v133, 0xbfb8aa3b, v133
	v_mul_f32_e32 v134, 0xbfb8aa3b, v134
	v_mul_f32_e32 v135, 0xbfb8aa3b, v135
	v_exp_f32_e32 v140, v140
	v_exp_f32_e32 v141, v141
	v_exp_f32_e32 v142, v142
	v_exp_f32_e32 v143, v143
	v_exp_f32_e32 v136, v136
	v_exp_f32_e32 v137, v137
	v_exp_f32_e32 v138, v138
	v_exp_f32_e32 v139, v139
	v_exp_f32_e32 v128, v128
	v_exp_f32_e32 v129, v129
	v_exp_f32_e32 v130, v130
	v_exp_f32_e32 v131, v131
	v_exp_f32_e32 v132, v132
	v_exp_f32_e32 v133, v133
	v_exp_f32_e32 v134, v134
	v_exp_f32_e32 v135, v135
	v_add_f32_e32 v140, 1.0, v140
	v_add_f32_e32 v141, 1.0, v141
	v_add_f32_e32 v142, 1.0, v142
	v_add_f32_e32 v143, 1.0, v143
	v_add_f32_e32 v136, 1.0, v136
	v_add_f32_e32 v137, 1.0, v137
	v_add_f32_e32 v138, 1.0, v138
	v_add_f32_e32 v139, 1.0, v139
	v_add_f32_e32 v128, 1.0, v128
	v_add_f32_e32 v129, 1.0, v129
	v_add_f32_e32 v130, 1.0, v130
	v_add_f32_e32 v131, 1.0, v131
	v_add_f32_e32 v132, 1.0, v132
	v_add_f32_e32 v133, 1.0, v133
	v_add_f32_e32 v134, 1.0, v134
	v_add_f32_e32 v135, 1.0, v135
	v_rcp_f32_e32 v140, v140
	v_rcp_f32_e32 v141, v141
	v_rcp_f32_e32 v142, v142
	v_rcp_f32_e32 v143, v143
	v_rcp_f32_e32 v136, v136
	v_rcp_f32_e32 v137, v137
	v_rcp_f32_e32 v138, v138
	v_rcp_f32_e32 v139, v139
	v_rcp_f32_e32 v172, v128
	v_rcp_f32_e32 v173, v129
	v_rcp_f32_e32 v184, v130
	v_rcp_f32_e32 v185, v131
	v_cvt_pk_bf16_f32 v128, v140, v141
	v_cvt_pk_bf16_f32 v129, v142, v143
	v_cvt_pk_bf16_f32 v130, v136, v137
	v_cvt_pk_bf16_f32 v131, v138, v139
	v_rcp_f32_e32 v132, v132
	v_rcp_f32_e32 v133, v133
	v_rcp_f32_e32 v134, v134
	v_rcp_f32_e32 v135, v135
	global_store_dwordx4 v[170:171], v[128:131], off
	s_nop 1
	v_cvt_pk_bf16_f32 v128, v132, v133
	v_cvt_pk_bf16_f32 v129, v134, v135
	v_cvt_pk_bf16_f32 v130, v172, v173
	v_cvt_pk_bf16_f32 v131, v184, v185
	s_cbranch_execnz .LBB0_239

; __device__ __forceinline__ unsigned pk2(float lo, float hi) { return pg8::cvt_pk_bf16(lo, hi); }
; __device__ __forceinline__ float rstd_of(float ssq) { return __builtin_amdgcn_rsqf(ssq * (1.0f / DM) + EPS); }
;     __device__ __forceinline__ void operator()(const f32x4 (&acc)[2][2][4][2], const Unit& u, int wr, int wc, int fr, int fq) const {
;     ...
;         if (pn < 8) {
;             const int sel = pn >> 1; bf16* base = sel == 0 ? U : sel == 1 ? Q : sel == 2 ? K : V; const float cs = sel == 1 ? C2Q : 1.0f;
;             const int cc = (pn & 1) * 256 + ct;
; #pragma unroll
;             for (int ai = 0; ai < 2; ++ai)
; #pragma unroll
;                 for (int m = 0; m < 4; ++m) { const int r = row0 + ai * 128 + m * 16; const float rs = rstd_of(ssq0[r]) * cs;
; #pragma unroll
;                     for (int bj = 0; bj < 2; ++bj) { const f32x4 v0 = acc[ai][bj][m][0] * rs, v1 = acc[ai][bj][m][1] * rs;
;                         u32x4 w; w.x = pk2(v0[0], v0[1]); w.y = pk2(v0[2], v0[3]); w.z = pk2(v1[0], v1[1]); w.w = pk2(v1[2], v1[3]);
;                         *(u32x4*)(base + (size_t)r * 512 + cc + bj * 128) = w; } }
.LBB0_250:
	v_lshl_add_u64 v[128:129], v[166:167], 2, s[14:15]
	s_nop 1
	s_cmp_eq_u32 s24, 1
	s_cselect_b64 vcc, -1, 0
	s_lshl_b32 s24, s95, 8
	s_and_b32 s24, s24, 0x100
	v_add_u32_e32 v134, s24, v177
	v_cndmask_b32_e32 v140, 1.0, v183, vcc
	v_lshlrev_b64 v[130:131], 10, v[166:167]
	v_lshl_add_u64 v[132:133], v[164:165], 2, s[14:15]
	s_waitcnt vmcnt(7)
	v_fmamk_f32 v135, v238, 0x3a800000, v182
	v_rsq_f32_e32 v136, v135
	v_ashrrev_i32_e32 v135, 31, v134
	v_lshl_add_u64 v[134:135], v[134:135], 1, s[56:57]
	v_lshl_add_u64 v[130:131], v[134:135], 0, v[130:131]
	v_mul_f32_e32 v136, v140, v136
	v_pk_mul_f32 v[126:127], v[126:127], v[136:137] op_sel_hi:[1,0]
	v_pk_mul_f32 v[124:125], v[124:125], v[136:137] op_sel_hi:[1,0]
	v_pk_mul_f32 v[122:123], v[122:123], v[136:137] op_sel_hi:[1,0]
	v_pk_mul_f32 v[120:121], v[120:121], v[136:137] op_sel_hi:[1,0]
	v_pk_mul_f32 v[118:119], v[118:119], v[136:137] op_sel_hi:[1,0]
	v_pk_mul_f32 v[116:117], v[116:117], v[136:137] op_sel_hi:[1,0]
	v_pk_mul_f32 v[138:139], v[114:115], v[136:137] op_sel_hi:[1,0]
	v_pk_mul_f32 v[136:137], v[112:113], v[136:137] op_sel_hi:[1,0]
	v_cvt_pk_bf16_f32 v112, v124, v125
	v_cvt_pk_bf16_f32 v113, v126, v127
	v_cvt_pk_bf16_f32 v114, v120, v121
	v_cvt_pk_bf16_f32 v115, v122, v123
	global_store_dwordx4 v[130:131], v[112:115], off
	v_lshl_add_u64 v[168:169], v[130:131], 0, s[46:47]
	s_nop 0
	v_cvt_pk_bf16_f32 v112, v116, v117
	v_cvt_pk_bf16_f32 v113, v118, v119
	v_cvt_pk_bf16_f32 v114, v136, v137
	v_cvt_pk_bf16_f32 v115, v138, v139
	global_store_dwordx4 v[130:131], v[112:115], off offset:256
	s_nop 1
	s_nop 0
	v_lshl_add_u64 v[114:115], v[162:163], 2, s[14:15]
	s_waitcnt vmcnt(8)
	v_fmamk_f32 v112, v239, 0x3a800000, v182
	v_rsq_f32_e32 v116, v112
	v_lshlrev_b64 v[112:113], 10, v[164:165]
	v_lshl_add_u64 v[112:113], v[134:135], 0, v[112:113]
	v_mul_f32_e32 v116, v140, v116
	v_pk_mul_f32 v[110:111], v[110:111], v[116:117] op_sel_hi:[1,0]
	v_pk_mul_f32 v[108:109], v[108:109], v[116:117] op_sel_hi:[1,0]
	v_pk_mul_f32 v[106:107], v[106:107], v[116:117] op_sel_hi:[1,0]
	v_pk_mul_f32 v[104:105], v[104:105], v[116:117] op_sel_hi:[1,0]
	v_pk_mul_f32 v[102:103], v[102:103], v[116:117] op_sel_hi:[1,0]
	v_pk_mul_f32 v[100:101], v[100:101], v[116:117] op_sel_hi:[1,0]
	v_pk_mul_f32 v[118:119], v[98:99], v[116:117] op_sel_hi:[1,0]
	v_pk_mul_f32 v[116:117], v[96:97], v[116:117] op_sel_hi:[1,0]
	v_cvt_pk_bf16_f32 v96, v108, v109
	v_cvt_pk_bf16_f32 v97, v110, v111
	v_cvt_pk_bf16_f32 v98, v104, v105
	v_cvt_pk_bf16_f32 v99, v106, v107
	global_store_dwordx4 v[112:113], v[96:99], off
	s_nop 1
	v_cvt_pk_bf16_f32 v96, v100, v101
	v_cvt_pk_bf16_f32 v97, v102, v103
	v_cvt_pk_bf16_f32 v98, v116, v117
	v_cvt_pk_bf16_f32 v99, v118, v119
	global_store_dwordx4 v[112:113], v[96:99], off offset:256
	s_nop 1
	s_nop 0
	v_lshl_add_u64 v[98:99], v[160:161], 2, s[14:15]
	s_waitcnt vmcnt(9)
	v_fmamk_f32 v96, v240, 0x3a800000, v182
	v_rsq_f32_e32 v100, v96
	v_lshlrev_b64 v[96:97], 10, v[162:163]
	v_lshl_add_u64 v[96:97], v[134:135], 0, v[96:97]
	v_mul_f32_e32 v100, v140, v100
	v_pk_mul_f32 v[94:95], v[94:95], v[100:101] op_sel_hi:[1,0]
	v_pk_mul_f32 v[92:93], v[92:93], v[100:101] op_sel_hi:[1,0]
	v_pk_mul_f32 v[90:91], v[90:91], v[100:101] op_sel_hi:[1,0]
	v_pk_mul_f32 v[88:89], v[88:89], v[100:101] op_sel_hi:[1,0]
	v_pk_mul_f32 v[82:83], v[82:83], v[100:101] op_sel_hi:[1,0]
	v_pk_mul_f32 v[80:81], v[80:81], v[100:101] op_sel_hi:[1,0]
	v_pk_mul_f32 v[102:103], v[78:79], v[100:101] op_sel_hi:[1,0]
	v_pk_mul_f32 v[100:101], v[76:77], v[100:101] op_sel_hi:[1,0]
	v_cvt_pk_bf16_f32 v76, v92, v93
	v_cvt_pk_bf16_f32 v77, v94, v95
	v_cvt_pk_bf16_f32 v78, v88, v89
	v_cvt_pk_bf16_f32 v79, v90, v91
	global_store_dwordx4 v[96:97], v[76:79], off
	s_nop 1
	v_cvt_pk_bf16_f32 v76, v80, v81
	v_cvt_pk_bf16_f32 v77, v82, v83
	v_cvt_pk_bf16_f32 v78, v100, v101
	v_cvt_pk_bf16_f32 v79, v102, v103
	global_store_dwordx4 v[96:97], v[76:79], off offset:256
	s_nop 1
	s_waitcnt vmcnt(10)
	v_fmamk_f32 v76, v241, 0x3a800000, v182
	v_rsq_f32_e32 v78, v76
	v_lshlrev_b64 v[76:77], 10, v[160:161]
	v_lshl_add_u64 v[76:77], v[134:135], 0, v[76:77]
	v_mul_f32_e32 v78, v140, v78
	v_pk_mul_f32 v[80:81], v[86:87], v[78:79] op_sel_hi:[1,0]
	v_pk_mul_f32 v[82:83], v[84:85], v[78:79] op_sel_hi:[1,0]
	v_pk_mul_f32 v[74:75], v[74:75], v[78:79] op_sel_hi:[1,0]
	v_pk_mul_f32 v[72:73], v[72:73], v[78:79] op_sel_hi:[1,0]
	v_pk_mul_f32 v[70:71], v[70:71], v[78:79] op_sel_hi:[1,0]
	v_pk_mul_f32 v[68:69], v[68:69], v[78:79] op_sel_hi:[1,0]
	v_pk_mul_f32 v[84:85], v[66:67], v[78:79] op_sel_hi:[1,0]
	v_pk_mul_f32 v[78:79], v[64:65], v[78:79] op_sel_hi:[1,0]
	v_cvt_pk_bf16_f32 v64, v82, v83
	v_cvt_pk_bf16_f32 v65, v80, v81
	v_cvt_pk_bf16_f32 v66, v72, v73
	v_cvt_pk_bf16_f32 v67, v74, v75
	global_store_dwordx4 v[76:77], v[64:67], off
	s_nop 1
	v_cvt_pk_bf16_f32 v64, v68, v69
	v_cvt_pk_bf16_f32 v65, v70, v71
	v_cvt_pk_bf16_f32 v66, v78, v79
	v_cvt_pk_bf16_f32 v67, v84, v85
	global_store_dwordx4 v[76:77], v[64:67], off offset:256
	s_nop 1
	s_nop 0
	v_lshl_add_u64 v[64:65], v[130:131], 0, s[40:41]
	s_waitcnt vmcnt(11)
; __device__ __forceinline__ unsigned pk2(float lo, float hi) { return pg8::cvt_pk_bf16(lo, hi); }
; __device__ __forceinline__ float rstd_of(float ssq) { return __builtin_amdgcn_rsqf(ssq * (1.0f / DM) + EPS); }
;     __device__ __forceinline__ void operator()(const f32x4 (&acc)[2][2][4][2], const Unit& u, int wr, int wc, int fr, int fq) const {
;     ...
;             for (int ai = 0; ai < 2; ++ai)
; #pragma unroll
;                 for (int m = 0; m < 4; ++m) { const int r = row0 + ai * 128 + m * 16; const float rs = rstd_of(ssq0[r]) * cs;
; #pragma unroll
;                     for (int bj = 0; bj < 2; ++bj) { const f32x4 v0 = acc[ai][bj][m][0] * rs, v1 = acc[ai][bj][m][1] * rs;
;                         u32x4 w; w.x = pk2(v0[0], v0[1]); w.y = pk2(v0[2], v0[3]); w.z = pk2(v1[0], v1[1]); w.w = pk2(v1[2], v1[3]);
;                         *(u32x4*)(base + (size_t)r * 512 + cc + bj * 128) = w; } }
	v_fmamk_f32 v66, v242, 0x3a800000, v182
	v_rsq_f32_e32 v68, v66
	v_add_co_u32_e32 v66, vcc, s91, v130
	v_mul_f32_e32 v68, v140, v68
	s_nop 0
	v_addc_co_u32_e32 v67, vcc, 0, v131, vcc
	v_pk_mul_f32 v[62:63], v[62:63], v[68:69] op_sel_hi:[1,0]
	v_pk_mul_f32 v[60:61], v[60:61], v[68:69] op_sel_hi:[1,0]
	v_pk_mul_f32 v[58:59], v[58:59], v[68:69] op_sel_hi:[1,0]
	v_pk_mul_f32 v[56:57], v[56:57], v[68:69] op_sel_hi:[1,0]
	v_pk_mul_f32 v[54:55], v[54:55], v[68:69] op_sel_hi:[1,0]
	v_pk_mul_f32 v[52:53], v[52:53], v[68:69] op_sel_hi:[1,0]
	v_pk_mul_f32 v[70:71], v[50:51], v[68:69] op_sel_hi:[1,0]
	v_pk_mul_f32 v[68:69], v[48:49], v[68:69] op_sel_hi:[1,0]
	v_cvt_pk_bf16_f32 v48, v60, v61
	v_cvt_pk_bf16_f32 v49, v62, v63
	v_cvt_pk_bf16_f32 v50, v56, v57
	v_cvt_pk_bf16_f32 v51, v58, v59
	global_store_dwordx4 v[66:67], v[48:51], off
	s_nop 1
	v_cvt_pk_bf16_f32 v48, v52, v53
	v_cvt_pk_bf16_f32 v49, v54, v55
	v_cvt_pk_bf16_f32 v50, v68, v69
	v_cvt_pk_bf16_f32 v51, v70, v71
	global_store_dwordx4 v[64:65], v[48:51], off offset:256
	s_nop 1
	s_nop 0
	v_lshl_add_u64 v[48:49], v[130:131], 0, s[42:43]
	s_waitcnt vmcnt(12)
	v_fmamk_f32 v50, v243, 0x3a800000, v182
	v_rsq_f32_e32 v52, v50
	v_add_co_u32_e32 v50, vcc, s92, v130
	v_mul_f32_e32 v52, v140, v52
	s_nop 0
	v_addc_co_u32_e32 v51, vcc, 0, v131, vcc
	v_pk_mul_f32 v[46:47], v[46:47], v[52:53] op_sel_hi:[1,0]
	v_pk_mul_f32 v[44:45], v[44:45], v[52:53] op_sel_hi:[1,0]
	v_pk_mul_f32 v[42:43], v[42:43], v[52:53] op_sel_hi:[1,0]
	v_pk_mul_f32 v[40:41], v[40:41], v[52:53] op_sel_hi:[1,0]
	v_pk_mul_f32 v[38:39], v[38:39], v[52:53] op_sel_hi:[1,0]
	v_pk_mul_f32 v[36:37], v[36:37], v[52:53] op_sel_hi:[1,0]
	v_pk_mul_f32 v[54:55], v[34:35], v[52:53] op_sel_hi:[1,0]
	v_pk_mul_f32 v[52:53], v[32:33], v[52:53] op_sel_hi:[1,0]
	v_cvt_pk_bf16_f32 v32, v44, v45
	v_cvt_pk_bf16_f32 v33, v46, v47
	v_cvt_pk_bf16_f32 v34, v40, v41
	v_cvt_pk_bf16_f32 v35, v42, v43
	global_store_dwordx4 v[50:51], v[32:35], off
	s_nop 1
	v_cvt_pk_bf16_f32 v32, v36, v37
	v_cvt_pk_bf16_f32 v33, v38, v39
	v_cvt_pk_bf16_f32 v34, v52, v53
	v_cvt_pk_bf16_f32 v35, v54, v55
	global_store_dwordx4 v[48:49], v[32:35], off offset:256
	s_nop 1
	s_nop 0
	v_lshl_add_u64 v[32:33], v[130:131], 0, s[44:45]
	s_waitcnt vmcnt(13)
	v_fmamk_f32 v34, v244, 0x3a800000, v182
	v_rsq_f32_e32 v36, v34
	v_add_co_u32_e32 v34, vcc, s93, v130
	v_mul_f32_e32 v36, v140, v36
	s_nop 0
	v_addc_co_u32_e32 v35, vcc, 0, v131, vcc
	v_pk_mul_f32 v[30:31], v[30:31], v[36:37] op_sel_hi:[1,0]
	v_pk_mul_f32 v[28:29], v[28:29], v[36:37] op_sel_hi:[1,0]
	v_pk_mul_f32 v[26:27], v[26:27], v[36:37] op_sel_hi:[1,0]
	v_pk_mul_f32 v[24:25], v[24:25], v[36:37] op_sel_hi:[1,0]
	v_pk_mul_f32 v[22:23], v[22:23], v[36:37] op_sel_hi:[1,0]
	v_pk_mul_f32 v[20:21], v[20:21], v[36:37] op_sel_hi:[1,0]
	v_pk_mul_f32 v[38:39], v[18:19], v[36:37] op_sel_hi:[1,0]
	v_pk_mul_f32 v[36:37], v[16:17], v[36:37] op_sel_hi:[1,0]
	v_cvt_pk_bf16_f32 v16, v28, v29
	v_cvt_pk_bf16_f32 v17, v30, v31
	v_cvt_pk_bf16_f32 v18, v24, v25
	v_cvt_pk_bf16_f32 v19, v26, v27
	global_store_dwordx4 v[34:35], v[16:19], off
	s_nop 1
	v_cvt_pk_bf16_f32 v16, v20, v21
	v_cvt_pk_bf16_f32 v17, v22, v23
	v_cvt_pk_bf16_f32 v18, v36, v37
	v_cvt_pk_bf16_f32 v19, v38, v39
	global_store_dwordx4 v[32:33], v[16:19], off offset:256
	s_nop 1
	s_waitcnt vmcnt(14)
	v_fmamk_f32 v16, v245, 0x3a800000, v182
	v_rsq_f32_e32 v18, v16
	v_add_co_u32_e32 v16, vcc, s94, v130
	v_mul_f32_e32 v18, v140, v18
	s_nop 0
	v_addc_co_u32_e32 v17, vcc, 0, v131, vcc
	v_pk_mul_f32 v[14:15], v[14:15], v[18:19] op_sel_hi:[1,0]
	v_pk_mul_f32 v[12:13], v[12:13], v[18:19] op_sel_hi:[1,0]
	v_pk_mul_f32 v[10:11], v[10:11], v[18:19] op_sel_hi:[1,0]
	v_pk_mul_f32 v[8:9], v[8:9], v[18:19] op_sel_hi:[1,0]
	v_pk_mul_f32 v[6:7], v[6:7], v[18:19] op_sel_hi:[1,0]
	v_pk_mul_f32 v[4:5], v[4:5], v[18:19] op_sel_hi:[1,0]
	v_pk_mul_f32 v[20:21], v[2:3], v[18:19] op_sel_hi:[1,0]
	v_pk_mul_f32 v[18:19], v[0:1], v[18:19] op_sel_hi:[1,0]
	v_cvt_pk_bf16_f32 v0, v12, v13
	v_cvt_pk_bf16_f32 v1, v14, v15
	v_cvt_pk_bf16_f32 v2, v8, v9
	v_cvt_pk_bf16_f32 v3, v10, v11
	global_store_dwordx4 v[16:17], v[0:3], off
	v_cvt_pk_bf16_f32 v128, v4, v5
	v_cvt_pk_bf16_f32 v129, v6, v7
	v_cvt_pk_bf16_f32 v130, v18, v19
	v_cvt_pk_bf16_f32 v131, v20, v21
	s_andn2_b64 vcc, exec, s[8:9]
	s_mov_b64 s[8:9], -1
	global_store_dwordx4 v[168:169], v[128:131], off offset:256
	s_cbranch_vccnz .LBB0_226
